# P3 merge epilogue rewritten: gate tile by LDS-DMA, 16-byte scratch accesses prefetched, straight-line per step, batched rows-out
# speedup vs baseline: 1.0110x; 1.0056x over previous
; DEV void tile_rows_in(const bf16_t* __restrict__ src0, const size_t ld, const int tid) {
; #pragma unroll 1
;   for (int io = 0; io < 4; ++io) {
;     u32x4 v[4];
; #pragma unroll
;     for (int ii = 0; ii < 4; ++ii) {
;       const int id = (io * 4 + ii) * 512 + tid, r = id >> 5, pos = id & 31, c = pos ^ (r & 31);
;       v[ii] = __builtin_nontemporal_load((const u32x4*)(src0 + (size_t)r * ld + 8 * c));
;     }
; #pragma unroll
;     for (int ii = 0; ii < 4; ++ii) {
;       const int id = (io * 4 + ii) * 512 + tid, r = id >> 5, pos = id & 31;
;       *(u32x4*)(smem + r * 512 + pos * 16) = v[ii];
;     }
;   }
; }
;   DEV void operator()(f32x4 (&acc)[2][2][4][2], int brow, int bcol, int wr, int wc, int fr, int fq) const {
;     const int tid = (wr * 4 + wc) * 64 + fq * 16 + fr;
;     u32x2* sp = (u32x2*)mg + ((size_t)((brow >> 8) * 8 + (bcol >> 8)) * 32) * 512 + tid;
;     tile_rows_in(gates + (size_t)brow * 6144 + gidx * 2048 + bcol, 6144, tid);
;     __syncthreads();
.LBB0_1291:
	s_or_b64 exec, exec, s[20:21]
	v_and_b32_e32 v128, 15, v140
	v_bfe_u32 v129, v140, 4, 2
	v_bfe_u32 v130, v140, 6, 2
	v_lshrrev_b32_e32 v131, 8, v140
	v_lshl_add_u32 v132, v131, 6, v128
	v_lshlrev_b32_e32 v132, 9, v132
	v_and_b32_e32 v133, 1, v129
	v_lshl_add_u32 v132, v133, 3, v132
	v_lshrrev_b32_e32 v133, 1, v129
	v_lshl_add_u32 v133, v130, 2, v133
	v_xor_b32_e32 v133, v133, v128
	v_lshl_add_u32 v134, v133, 4, v132
	v_xor_b32_e32 v133, 2, v133
	v_lshl_add_u32 v135, v133, 4, v132
	v_add_u32_e32 v136, 0x10000, v134
	v_add_u32_e32 v137, 0x10000, v135
	v_readlane_b32 s22, v253, 10
	s_ashr_i32 s21, s4, 5
	s_and_b32 s21, s21, -8
	s_ashr_i32 s20, s34, 8
	s_add_i32 s20, s21, s20
	s_ashr_i32 s21, s20, 31
	s_lshl_b64 s[20:21], s[20:21], 17
	s_add_u32 s20, s76, s20
	s_addc_u32 s21, s22, s21
	v_lshlrev_b32_e32 v141, 4, v140
	s_cmp_lt_i32 s37, 1
	s_cbranch_scc1 .Lp3l_nopf
	global_load_dwordx4 v[160:163], v141, s[20:21]
	v_add_u32_e32 v141, 0x2000, v141
	global_load_dwordx4 v[164:167], v141, s[20:21]
	v_add_u32_e32 v141, 0x2000, v141
	global_load_dwordx4 v[168:171], v141, s[20:21]
	v_add_u32_e32 v141, 0x2000, v141
	global_load_dwordx4 v[172:175], v141, s[20:21]
	v_add_u32_e32 v141, 0x2000, v141
	global_load_dwordx4 v[184:187], v141, s[20:21]
	v_add_u32_e32 v141, 0x2000, v141
	global_load_dwordx4 v[188:191], v141, s[20:21]
	v_add_u32_e32 v141, 0x2000, v141
	global_load_dwordx4 v[192:195], v141, s[20:21]
	v_add_u32_e32 v141, 0x2000, v141
	global_load_dwordx4 v[200:203], v141, s[20:21]
	v_add_u32_e32 v141, 0x2000, v141
	global_load_dwordx4 v[204:207], v141, s[20:21]
	v_add_u32_e32 v141, 0x2000, v141
	global_load_dwordx4 v[208:211], v141, s[20:21]
	v_add_u32_e32 v141, 0x2000, v141
	global_load_dwordx4 v[212:215], v141, s[20:21]
	v_add_u32_e32 v141, 0x2000, v141
	global_load_dwordx4 v[224:227], v141, s[20:21]
	v_add_u32_e32 v141, 0x2000, v141
	global_load_dwordx4 v[228:231], v141, s[20:21]
	v_add_u32_e32 v141, 0x2000, v141
	global_load_dwordx4 v[232:235], v141, s[20:21]
	v_add_u32_e32 v141, 0x2000, v141
	global_load_dwordx4 v[236:239], v141, s[20:21]
	v_add_u32_e32 v141, 0x2000, v141
	global_load_dwordx4 v[240:243], v141, s[20:21]
.Lp3l_nopf:
	v_readlane_b32 s22, v253, 8
	v_readlane_b32 s23, v253, 9
	s_mul_i32 s24, s4, 0x3000
	s_lshl_b32 s25, s34, 1
	s_add_i32 s24, s24, s25
	s_cmp_eq_u32 s37, 0
	s_cselect_b32 s25, 0x1000, 0
	s_cmp_eq_u32 s37, 1
	s_cselect_b32 s25, 0x2000, s25
	s_add_i32 s24, s24, s25
	s_add_u32 s22, s22, s24
	s_addc_u32 s23, s23, 0
	v_lshrrev_b32_e32 v144, 5, v140
	v_and_b32_e32 v145, 31, v140
	v_xor_b32_e32 v145, v145, v144
	v_mul_u32_u24_e32 v142, 0x3000, v144
	v_mov_b32_e32 v143, v142
	v_lshl_add_u32 v142, v145, 4, v142
	v_xor_b32_e32 v145, 16, v145
	v_lshl_add_u32 v143, v145, 4, v143
	v_add_u32_e32 v143, 0x30000, v143
	v_lshrrev_b32_e32 v144, 6, v140
	v_lshlrev_b32_e32 v144, 10, v144
	s_nop 0
	v_readfirstlane_b32 s24, v144
	s_mov_b32 m0, s24
	s_nop 0
	global_load_lds_dwordx4 v142, s[22:23] nt
	s_add_i32 m0, m0, 0x2000
	v_add_u32_e32 v142, 0x60000, v142
	global_load_lds_dwordx4 v143, s[22:23] nt
	s_add_i32 m0, m0, 0x2000
	v_add_u32_e32 v143, 0x60000, v143
	global_load_lds_dwordx4 v142, s[22:23] nt
	s_add_i32 m0, m0, 0x2000
	v_add_u32_e32 v142, 0x60000, v142
	global_load_lds_dwordx4 v143, s[22:23] nt
	s_add_i32 m0, m0, 0x2000
	v_add_u32_e32 v143, 0x60000, v143
	global_load_lds_dwordx4 v142, s[22:23] nt
	s_add_i32 m0, m0, 0x2000
	v_add_u32_e32 v142, 0x60000, v142
	global_load_lds_dwordx4 v143, s[22:23] nt
	s_add_i32 m0, m0, 0x2000
	v_add_u32_e32 v143, 0x60000, v143
	global_load_lds_dwordx4 v142, s[22:23] nt
	s_add_i32 m0, m0, 0x2000
	v_add_u32_e32 v142, 0x60000, v142
	global_load_lds_dwordx4 v143, s[22:23] nt
	s_add_i32 m0, m0, 0x2000
	v_add_u32_e32 v143, 0x60000, v143
	global_load_lds_dwordx4 v142, s[22:23] nt
	s_add_i32 m0, m0, 0x2000
	v_add_u32_e32 v142, 0x60000, v142
	global_load_lds_dwordx4 v143, s[22:23] nt
	s_add_i32 m0, m0, 0x2000
	v_add_u32_e32 v143, 0x60000, v143
	global_load_lds_dwordx4 v142, s[22:23] nt
	s_add_i32 m0, m0, 0x2000
	v_add_u32_e32 v142, 0x60000, v142
	global_load_lds_dwordx4 v143, s[22:23] nt
	s_add_i32 m0, m0, 0x2000
	v_add_u32_e32 v143, 0x60000, v143
	global_load_lds_dwordx4 v142, s[22:23] nt
	s_add_i32 m0, m0, 0x2000
	v_add_u32_e32 v142, 0x60000, v142
	global_load_lds_dwordx4 v143, s[22:23] nt
	s_add_i32 m0, m0, 0x2000
	v_add_u32_e32 v143, 0x60000, v143
	global_load_lds_dwordx4 v142, s[22:23] nt
	s_add_i32 m0, m0, 0x2000
	s_nop 0
	global_load_lds_dwordx4 v143, s[22:23] nt
	s_waitcnt vmcnt(0)
	s_barrier
	s_cmp_eq_u32 s37, 1
	s_cbranch_scc1 .Lp3l_step1
	s_cmp_eq_u32 s37, 2
	s_cbranch_scc1 .Lp3l_step2
; DEV u32x2 pk4(f32x4 v) { u32x2 r = {pk_bf16(v[0], v[1]), pk_bf16(v[2], v[3])}; return r; }
; DEV f32x4 unpk4(u32x2 u) { f32x4 r = {bf_lo(u[0]), bf_hi(u[0]), bf_lo(u[1]), bf_hi(u[1])}; return r; }
;   DEV void operator()(f32x4 (&acc)[2][2][4][2], int brow, int bcol, int wr, int wc, int fr, int fq) const {
;     ...
;     for (int ai = 0; ai < 2; ++ai)
; #pragma unroll
;       for (int m = 0; m < 4; ++m) {
;         const int rl = ai * 128 + wr * 64 + m * 16 + fr, tok = brow + rl;
; #pragma unroll
;         for (int bj = 0; bj < 2; ++bj)
; #pragma unroll
;           for (int n = 0; n < 2; ++n) {
;             const int cl = bj * 128 + wc * 32 + n * 16 + fq * 4, col = bcol + cl;
;             const int f = ((ai * 4 + m) * 2 + bj) * 2 + n;
;             const f32x4 g = unpk4(tile_get4(rl, cl));
;             f32x4 v = acc[ai][bj][m][n] * g;
;             if (step == 0) sp[(size_t)f * 512] = pk4(v);
	ds_read_b64 v[244:245], v134
	ds_read_b64 v[246:247], v135
	ds_read_b64 v[248:249], v134 offset:256
	ds_read_b64 v[250:251], v135 offset:256
	s_waitcnt lgkmcnt(3)
	v_lshlrev_b32_e32 v146, 16, v244
	v_and_b32_e32 v147, 0xffff0000, v244
	v_lshlrev_b32_e32 v148, 16, v245
	v_and_b32_e32 v149, 0xffff0000, v245
	v_pk_mul_f32 v[124:125], v[124:125], v[146:147]
	v_pk_mul_f32 v[126:127], v[126:127], v[148:149]
	v_cvt_pk_bf16_f32 v124, v124, v125
	v_cvt_pk_bf16_f32 v125, v126, v127
	s_waitcnt lgkmcnt(2)
	v_lshlrev_b32_e32 v146, 16, v246
	v_and_b32_e32 v147, 0xffff0000, v246
	v_lshlrev_b32_e32 v148, 16, v247
	v_and_b32_e32 v149, 0xffff0000, v247
	v_pk_mul_f32 v[120:121], v[120:121], v[146:147]
	v_pk_mul_f32 v[122:123], v[122:123], v[148:149]
	v_cvt_pk_bf16_f32 v126, v120, v121
	v_cvt_pk_bf16_f32 v127, v122, v123
	s_waitcnt lgkmcnt(1)
	v_lshlrev_b32_e32 v146, 16, v248
	v_and_b32_e32 v147, 0xffff0000, v248
	v_lshlrev_b32_e32 v148, 16, v249
	v_and_b32_e32 v149, 0xffff0000, v249
	v_pk_mul_f32 v[116:117], v[116:117], v[146:147]
	v_pk_mul_f32 v[118:119], v[118:119], v[148:149]
	v_cvt_pk_bf16_f32 v116, v116, v117
	v_cvt_pk_bf16_f32 v117, v118, v119
	s_waitcnt lgkmcnt(0)
	v_lshlrev_b32_e32 v146, 16, v250
	v_and_b32_e32 v147, 0xffff0000, v250
	v_lshlrev_b32_e32 v148, 16, v251
	v_and_b32_e32 v149, 0xffff0000, v251
	v_pk_mul_f32 v[112:113], v[112:113], v[146:147]
	v_pk_mul_f32 v[114:115], v[114:115], v[148:149]
	v_cvt_pk_bf16_f32 v118, v112, v113
	v_cvt_pk_bf16_f32 v119, v114, v115
	ds_read_b64 v[244:245], v134 offset:8448
	ds_read_b64 v[246:247], v135 offset:8448
	ds_read_b64 v[248:249], v134 offset:8192
	ds_read_b64 v[250:251], v135 offset:8192
	s_waitcnt lgkmcnt(3)
	v_lshlrev_b32_e32 v146, 16, v244
	v_and_b32_e32 v147, 0xffff0000, v244
	v_lshlrev_b32_e32 v148, 16, v245
	v_and_b32_e32 v149, 0xffff0000, v245
	v_pk_mul_f32 v[108:109], v[108:109], v[146:147]
	v_pk_mul_f32 v[110:111], v[110:111], v[148:149]
	v_cvt_pk_bf16_f32 v108, v108, v109
	v_cvt_pk_bf16_f32 v109, v110, v111
	s_waitcnt lgkmcnt(2)
	v_lshlrev_b32_e32 v146, 16, v246
	v_and_b32_e32 v147, 0xffff0000, v246
	v_lshlrev_b32_e32 v148, 16, v247
	v_and_b32_e32 v149, 0xffff0000, v247
	v_pk_mul_f32 v[104:105], v[104:105], v[146:147]
	v_pk_mul_f32 v[106:107], v[106:107], v[148:149]
	v_cvt_pk_bf16_f32 v110, v104, v105
	v_cvt_pk_bf16_f32 v111, v106, v107
	s_waitcnt lgkmcnt(1)
	v_lshlrev_b32_e32 v146, 16, v248
	v_and_b32_e32 v147, 0xffff0000, v248
	v_lshlrev_b32_e32 v148, 16, v249
	v_and_b32_e32 v149, 0xffff0000, v249
	v_pk_mul_f32 v[100:101], v[100:101], v[146:147]
	v_pk_mul_f32 v[102:103], v[102:103], v[148:149]
	v_cvt_pk_bf16_f32 v100, v100, v101
	v_cvt_pk_bf16_f32 v101, v102, v103
	s_waitcnt lgkmcnt(0)
	v_lshlrev_b32_e32 v146, 16, v250
	v_and_b32_e32 v147, 0xffff0000, v250
	v_lshlrev_b32_e32 v148, 16, v251
	v_and_b32_e32 v149, 0xffff0000, v251
	v_pk_mul_f32 v[96:97], v[96:97], v[146:147]
	v_pk_mul_f32 v[98:99], v[98:99], v[148:149]
	v_cvt_pk_bf16_f32 v102, v96, v97
	v_cvt_pk_bf16_f32 v103, v98, v99
	ds_read_b64 v[244:245], v134 offset:16384
	ds_read_b64 v[246:247], v135 offset:16384
	ds_read_b64 v[248:249], v134 offset:16640
	ds_read_b64 v[250:251], v135 offset:16640
	s_waitcnt lgkmcnt(3)
	v_lshlrev_b32_e32 v146, 16, v244
	v_and_b32_e32 v147, 0xffff0000, v244
	v_lshlrev_b32_e32 v148, 16, v245
	v_and_b32_e32 v149, 0xffff0000, v245
	v_pk_mul_f32 v[92:93], v[92:93], v[146:147]
	v_pk_mul_f32 v[94:95], v[94:95], v[148:149]
	v_cvt_pk_bf16_f32 v92, v92, v93
	v_cvt_pk_bf16_f32 v93, v94, v95
	s_waitcnt lgkmcnt(2)
	v_lshlrev_b32_e32 v146, 16, v246
	v_and_b32_e32 v147, 0xffff0000, v246
	v_lshlrev_b32_e32 v148, 16, v247
	v_and_b32_e32 v149, 0xffff0000, v247
	v_pk_mul_f32 v[88:89], v[88:89], v[146:147]
	v_pk_mul_f32 v[90:91], v[90:91], v[148:149]
	v_cvt_pk_bf16_f32 v94, v88, v89
	v_cvt_pk_bf16_f32 v95, v90, v91
	s_waitcnt lgkmcnt(1)
	v_lshlrev_b32_e32 v146, 16, v248
	v_and_b32_e32 v147, 0xffff0000, v248
	v_lshlrev_b32_e32 v148, 16, v249
	v_and_b32_e32 v149, 0xffff0000, v249
	v_pk_mul_f32 v[84:85], v[84:85], v[146:147]
	v_pk_mul_f32 v[86:87], v[86:87], v[148:149]
	v_cvt_pk_bf16_f32 v84, v84, v85
	v_cvt_pk_bf16_f32 v85, v86, v87
	s_waitcnt lgkmcnt(0)
	v_lshlrev_b32_e32 v146, 16, v250
	v_and_b32_e32 v147, 0xffff0000, v250
	v_lshlrev_b32_e32 v148, 16, v251
	v_and_b32_e32 v149, 0xffff0000, v251
	v_pk_mul_f32 v[80:81], v[80:81], v[146:147]
	v_pk_mul_f32 v[82:83], v[82:83], v[148:149]
	v_cvt_pk_bf16_f32 v86, v80, v81
	v_cvt_pk_bf16_f32 v87, v82, v83
	ds_read_b64 v[244:245], v134 offset:24832
	ds_read_b64 v[246:247], v135 offset:24832
	ds_read_b64 v[248:249], v134 offset:24576
	ds_read_b64 v[250:251], v135 offset:24576
	s_waitcnt lgkmcnt(3)
	v_lshlrev_b32_e32 v146, 16, v244
	v_and_b32_e32 v147, 0xffff0000, v244
	v_lshlrev_b32_e32 v148, 16, v245
	v_and_b32_e32 v149, 0xffff0000, v245
	v_pk_mul_f32 v[76:77], v[76:77], v[146:147]
	v_pk_mul_f32 v[78:79], v[78:79], v[148:149]
	v_cvt_pk_bf16_f32 v76, v76, v77
	v_cvt_pk_bf16_f32 v77, v78, v79
	s_waitcnt lgkmcnt(2)
	v_lshlrev_b32_e32 v146, 16, v246
	v_and_b32_e32 v147, 0xffff0000, v246
	v_lshlrev_b32_e32 v148, 16, v247
	v_and_b32_e32 v149, 0xffff0000, v247
	v_pk_mul_f32 v[72:73], v[72:73], v[146:147]
	v_pk_mul_f32 v[74:75], v[74:75], v[148:149]
	v_cvt_pk_bf16_f32 v78, v72, v73
	v_cvt_pk_bf16_f32 v79, v74, v75
	s_waitcnt lgkmcnt(1)
	v_lshlrev_b32_e32 v146, 16, v248
	v_and_b32_e32 v147, 0xffff0000, v248
	v_lshlrev_b32_e32 v148, 16, v249
	v_and_b32_e32 v149, 0xffff0000, v249
	v_pk_mul_f32 v[68:69], v[68:69], v[146:147]
	v_pk_mul_f32 v[70:71], v[70:71], v[148:149]
	v_cvt_pk_bf16_f32 v68, v68, v69
	v_cvt_pk_bf16_f32 v69, v70, v71
	s_waitcnt lgkmcnt(0)
; DEV u32x2 pk4(f32x4 v) { u32x2 r = {pk_bf16(v[0], v[1]), pk_bf16(v[2], v[3])}; return r; }
; DEV f32x4 unpk4(u32x2 u) { f32x4 r = {bf_lo(u[0]), bf_hi(u[0]), bf_lo(u[1]), bf_hi(u[1])}; return r; }
;   DEV void operator()(f32x4 (&acc)[2][2][4][2], int brow, int bcol, int wr, int wc, int fr, int fq) const {
;     ...
;     for (int ai = 0; ai < 2; ++ai)
; #pragma unroll
;       for (int m = 0; m < 4; ++m) {
;         const int rl = ai * 128 + wr * 64 + m * 16 + fr, tok = brow + rl;
; #pragma unroll
;         for (int bj = 0; bj < 2; ++bj)
; #pragma unroll
;           for (int n = 0; n < 2; ++n) {
;             const int cl = bj * 128 + wc * 32 + n * 16 + fq * 4, col = bcol + cl;
;             const int f = ((ai * 4 + m) * 2 + bj) * 2 + n;
;             const f32x4 g = unpk4(tile_get4(rl, cl));
;             f32x4 v = acc[ai][bj][m][n] * g;
;             if (step == 0) sp[(size_t)f * 512] = pk4(v);
	v_lshlrev_b32_e32 v146, 16, v250
	v_and_b32_e32 v147, 0xffff0000, v250
	v_lshlrev_b32_e32 v148, 16, v251
	v_and_b32_e32 v149, 0xffff0000, v251
	v_pk_mul_f32 v[64:65], v[64:65], v[146:147]
	v_pk_mul_f32 v[66:67], v[66:67], v[148:149]
	v_cvt_pk_bf16_f32 v70, v64, v65
	v_cvt_pk_bf16_f32 v71, v66, v67
	ds_read_b64 v[244:245], v136
	ds_read_b64 v[246:247], v137
	ds_read_b64 v[248:249], v136 offset:256
	ds_read_b64 v[250:251], v137 offset:256
	s_waitcnt lgkmcnt(3)
	v_lshlrev_b32_e32 v146, 16, v244
	v_and_b32_e32 v147, 0xffff0000, v244
	v_lshlrev_b32_e32 v148, 16, v245
	v_and_b32_e32 v149, 0xffff0000, v245
	v_pk_mul_f32 v[60:61], v[60:61], v[146:147]
	v_pk_mul_f32 v[62:63], v[62:63], v[148:149]
	v_cvt_pk_bf16_f32 v60, v60, v61
	v_cvt_pk_bf16_f32 v61, v62, v63
	s_waitcnt lgkmcnt(2)
	v_lshlrev_b32_e32 v146, 16, v246
	v_and_b32_e32 v147, 0xffff0000, v246
	v_lshlrev_b32_e32 v148, 16, v247
	v_and_b32_e32 v149, 0xffff0000, v247
	v_pk_mul_f32 v[56:57], v[56:57], v[146:147]
	v_pk_mul_f32 v[58:59], v[58:59], v[148:149]
	v_cvt_pk_bf16_f32 v62, v56, v57
	v_cvt_pk_bf16_f32 v63, v58, v59
	s_waitcnt lgkmcnt(1)
	v_lshlrev_b32_e32 v146, 16, v248
	v_and_b32_e32 v147, 0xffff0000, v248
	v_lshlrev_b32_e32 v148, 16, v249
	v_and_b32_e32 v149, 0xffff0000, v249
	v_pk_mul_f32 v[52:53], v[52:53], v[146:147]
	v_pk_mul_f32 v[54:55], v[54:55], v[148:149]
	v_cvt_pk_bf16_f32 v52, v52, v53
	v_cvt_pk_bf16_f32 v53, v54, v55
	s_waitcnt lgkmcnt(0)
	v_lshlrev_b32_e32 v146, 16, v250
	v_and_b32_e32 v147, 0xffff0000, v250
	v_lshlrev_b32_e32 v148, 16, v251
	v_and_b32_e32 v149, 0xffff0000, v251
	v_pk_mul_f32 v[48:49], v[48:49], v[146:147]
	v_pk_mul_f32 v[50:51], v[50:51], v[148:149]
	v_cvt_pk_bf16_f32 v54, v48, v49
	v_cvt_pk_bf16_f32 v55, v50, v51
	ds_read_b64 v[244:245], v136 offset:8448
	ds_read_b64 v[246:247], v137 offset:8448
	ds_read_b64 v[248:249], v136 offset:8192
	ds_read_b64 v[250:251], v137 offset:8192
	s_waitcnt lgkmcnt(3)
	v_lshlrev_b32_e32 v146, 16, v244
	v_and_b32_e32 v147, 0xffff0000, v244
	v_lshlrev_b32_e32 v148, 16, v245
	v_and_b32_e32 v149, 0xffff0000, v245
	v_pk_mul_f32 v[44:45], v[44:45], v[146:147]
	v_pk_mul_f32 v[46:47], v[46:47], v[148:149]
	v_cvt_pk_bf16_f32 v44, v44, v45
	v_cvt_pk_bf16_f32 v45, v46, v47
	s_waitcnt lgkmcnt(2)
	v_lshlrev_b32_e32 v146, 16, v246
	v_and_b32_e32 v147, 0xffff0000, v246
	v_lshlrev_b32_e32 v148, 16, v247
	v_and_b32_e32 v149, 0xffff0000, v247
	v_pk_mul_f32 v[40:41], v[40:41], v[146:147]
	v_pk_mul_f32 v[42:43], v[42:43], v[148:149]
	v_cvt_pk_bf16_f32 v46, v40, v41
	v_cvt_pk_bf16_f32 v47, v42, v43
	s_waitcnt lgkmcnt(1)
	v_lshlrev_b32_e32 v146, 16, v248
	v_and_b32_e32 v147, 0xffff0000, v248
	v_lshlrev_b32_e32 v148, 16, v249
	v_and_b32_e32 v149, 0xffff0000, v249
	v_pk_mul_f32 v[36:37], v[36:37], v[146:147]
	v_pk_mul_f32 v[38:39], v[38:39], v[148:149]
	v_cvt_pk_bf16_f32 v36, v36, v37
	v_cvt_pk_bf16_f32 v37, v38, v39
	s_waitcnt lgkmcnt(0)
	v_lshlrev_b32_e32 v146, 16, v250
	v_and_b32_e32 v147, 0xffff0000, v250
	v_lshlrev_b32_e32 v148, 16, v251
	v_and_b32_e32 v149, 0xffff0000, v251
	v_pk_mul_f32 v[32:33], v[32:33], v[146:147]
	v_pk_mul_f32 v[34:35], v[34:35], v[148:149]
	v_cvt_pk_bf16_f32 v38, v32, v33
	v_cvt_pk_bf16_f32 v39, v34, v35
	ds_read_b64 v[244:245], v136 offset:16384
	ds_read_b64 v[246:247], v137 offset:16384
	ds_read_b64 v[248:249], v136 offset:16640
	ds_read_b64 v[250:251], v137 offset:16640
	s_waitcnt lgkmcnt(3)
	v_lshlrev_b32_e32 v146, 16, v244
	v_and_b32_e32 v147, 0xffff0000, v244
	v_lshlrev_b32_e32 v148, 16, v245
	v_and_b32_e32 v149, 0xffff0000, v245
	v_pk_mul_f32 v[28:29], v[28:29], v[146:147]
	v_pk_mul_f32 v[30:31], v[30:31], v[148:149]
	v_cvt_pk_bf16_f32 v28, v28, v29
	v_cvt_pk_bf16_f32 v29, v30, v31
	s_waitcnt lgkmcnt(2)
	v_lshlrev_b32_e32 v146, 16, v246
	v_and_b32_e32 v147, 0xffff0000, v246
	v_lshlrev_b32_e32 v148, 16, v247
	v_and_b32_e32 v149, 0xffff0000, v247
	v_pk_mul_f32 v[24:25], v[24:25], v[146:147]
	v_pk_mul_f32 v[26:27], v[26:27], v[148:149]
	v_cvt_pk_bf16_f32 v30, v24, v25
	v_cvt_pk_bf16_f32 v31, v26, v27
	s_waitcnt lgkmcnt(1)
	v_lshlrev_b32_e32 v146, 16, v248
	v_and_b32_e32 v147, 0xffff0000, v248
	v_lshlrev_b32_e32 v148, 16, v249
	v_and_b32_e32 v149, 0xffff0000, v249
	v_pk_mul_f32 v[20:21], v[20:21], v[146:147]
	v_pk_mul_f32 v[22:23], v[22:23], v[148:149]
	v_cvt_pk_bf16_f32 v20, v20, v21
	v_cvt_pk_bf16_f32 v21, v22, v23
	s_waitcnt lgkmcnt(0)
	v_lshlrev_b32_e32 v146, 16, v250
	v_and_b32_e32 v147, 0xffff0000, v250
	v_lshlrev_b32_e32 v148, 16, v251
	v_and_b32_e32 v149, 0xffff0000, v251
	v_pk_mul_f32 v[16:17], v[16:17], v[146:147]
	v_pk_mul_f32 v[18:19], v[18:19], v[148:149]
	v_cvt_pk_bf16_f32 v22, v16, v17
	v_cvt_pk_bf16_f32 v23, v18, v19
	ds_read_b64 v[244:245], v136 offset:24832
	ds_read_b64 v[246:247], v137 offset:24832
	ds_read_b64 v[248:249], v136 offset:24576
	ds_read_b64 v[250:251], v137 offset:24576
	s_waitcnt lgkmcnt(3)
	v_lshlrev_b32_e32 v146, 16, v244
	v_and_b32_e32 v147, 0xffff0000, v244
	v_lshlrev_b32_e32 v148, 16, v245
	v_and_b32_e32 v149, 0xffff0000, v245
	v_pk_mul_f32 v[12:13], v[12:13], v[146:147]
	v_pk_mul_f32 v[14:15], v[14:15], v[148:149]
	v_cvt_pk_bf16_f32 v12, v12, v13
	v_cvt_pk_bf16_f32 v13, v14, v15
	s_waitcnt lgkmcnt(2)
	v_lshlrev_b32_e32 v146, 16, v246
	v_and_b32_e32 v147, 0xffff0000, v246
	v_lshlrev_b32_e32 v148, 16, v247
	v_and_b32_e32 v149, 0xffff0000, v247
	v_pk_mul_f32 v[8:9], v[8:9], v[146:147]
	v_pk_mul_f32 v[10:11], v[10:11], v[148:149]
	v_cvt_pk_bf16_f32 v14, v8, v9
	v_cvt_pk_bf16_f32 v15, v10, v11
	s_waitcnt lgkmcnt(1)
	v_lshlrev_b32_e32 v146, 16, v248
	v_and_b32_e32 v147, 0xffff0000, v248
	v_lshlrev_b32_e32 v148, 16, v249
	v_and_b32_e32 v149, 0xffff0000, v249
	v_pk_mul_f32 v[4:5], v[4:5], v[146:147]
	v_pk_mul_f32 v[6:7], v[6:7], v[148:149]
	v_cvt_pk_bf16_f32 v4, v4, v5
	v_cvt_pk_bf16_f32 v5, v6, v7
	s_waitcnt lgkmcnt(0)
; DEV u32x2 pk4(f32x4 v) { u32x2 r = {pk_bf16(v[0], v[1]), pk_bf16(v[2], v[3])}; return r; }
; DEV f32x4 unpk4(u32x2 u) { f32x4 r = {bf_lo(u[0]), bf_hi(u[0]), bf_lo(u[1]), bf_hi(u[1])}; return r; }
;   DEV void operator()(f32x4 (&acc)[2][2][4][2], int brow, int bcol, int wr, int wc, int fr, int fq) const {
;     ...
;     for (int ai = 0; ai < 2; ++ai)
; #pragma unroll
;       for (int m = 0; m < 4; ++m) {
;         const int rl = ai * 128 + wr * 64 + m * 16 + fr, tok = brow + rl;
; #pragma unroll
;         for (int bj = 0; bj < 2; ++bj)
; #pragma unroll
;           for (int n = 0; n < 2; ++n) {
;             const int cl = bj * 128 + wc * 32 + n * 16 + fq * 4, col = bcol + cl;
;             const int f = ((ai * 4 + m) * 2 + bj) * 2 + n;
;             const f32x4 g = unpk4(tile_get4(rl, cl));
;             f32x4 v = acc[ai][bj][m][n] * g;
;             if (step == 0) sp[(size_t)f * 512] = pk4(v);
;             else if (step == 1) sp[(size_t)f * 512] = pk4(unpk4(sp[(size_t)f * 512]) + v);
	v_lshlrev_b32_e32 v146, 16, v250
	v_and_b32_e32 v147, 0xffff0000, v250
	v_lshlrev_b32_e32 v148, 16, v251
	v_and_b32_e32 v149, 0xffff0000, v251
	v_pk_mul_f32 v[0:1], v[0:1], v[146:147]
	v_pk_mul_f32 v[2:3], v[2:3], v[148:149]
	v_cvt_pk_bf16_f32 v6, v0, v1
	v_cvt_pk_bf16_f32 v7, v2, v3
	v_lshlrev_b32_e32 v141, 4, v140
	global_store_dwordx4 v141, v[124:127], s[20:21]
	v_add_u32_e32 v141, 0x2000, v141
	global_store_dwordx4 v141, v[116:119], s[20:21]
	v_add_u32_e32 v141, 0x2000, v141
	global_store_dwordx4 v141, v[108:111], s[20:21]
	v_add_u32_e32 v141, 0x2000, v141
	global_store_dwordx4 v141, v[100:103], s[20:21]
	v_add_u32_e32 v141, 0x2000, v141
	global_store_dwordx4 v141, v[92:95], s[20:21]
	v_add_u32_e32 v141, 0x2000, v141
	global_store_dwordx4 v141, v[84:87], s[20:21]
	v_add_u32_e32 v141, 0x2000, v141
	global_store_dwordx4 v141, v[76:79], s[20:21]
	v_add_u32_e32 v141, 0x2000, v141
	global_store_dwordx4 v141, v[68:71], s[20:21]
	v_add_u32_e32 v141, 0x2000, v141
	global_store_dwordx4 v141, v[60:63], s[20:21]
	v_add_u32_e32 v141, 0x2000, v141
	global_store_dwordx4 v141, v[52:55], s[20:21]
	v_add_u32_e32 v141, 0x2000, v141
	global_store_dwordx4 v141, v[44:47], s[20:21]
	v_add_u32_e32 v141, 0x2000, v141
	global_store_dwordx4 v141, v[36:39], s[20:21]
	v_add_u32_e32 v141, 0x2000, v141
	global_store_dwordx4 v141, v[28:31], s[20:21]
	v_add_u32_e32 v141, 0x2000, v141
	global_store_dwordx4 v141, v[20:23], s[20:21]
	v_add_u32_e32 v141, 0x2000, v141
	global_store_dwordx4 v141, v[12:15], s[20:21]
	v_add_u32_e32 v141, 0x2000, v141
	global_store_dwordx4 v141, v[4:7], s[20:21]
	s_branch .LBB0_1272
.Lp3l_step1:
	ds_read_b64 v[244:245], v134
	ds_read_b64 v[246:247], v135
	ds_read_b64 v[248:249], v134 offset:256
	ds_read_b64 v[250:251], v135 offset:256
	s_waitcnt lgkmcnt(3)
	v_lshlrev_b32_e32 v146, 16, v244
	v_and_b32_e32 v147, 0xffff0000, v244
	v_lshlrev_b32_e32 v148, 16, v245
	v_and_b32_e32 v149, 0xffff0000, v245
	v_pk_mul_f32 v[124:125], v[124:125], v[146:147]
	v_pk_mul_f32 v[126:127], v[126:127], v[148:149]
	v_lshlrev_b32_e32 v150, 16, v160
	v_and_b32_e32 v151, 0xffff0000, v160
	v_lshlrev_b32_e32 v152, 16, v161
	v_and_b32_e32 v153, 0xffff0000, v161
	v_pk_add_f32 v[124:125], v[124:125], v[150:151]
	v_pk_add_f32 v[126:127], v[126:127], v[152:153]
	v_cvt_pk_bf16_f32 v124, v124, v125
	v_cvt_pk_bf16_f32 v125, v126, v127
	s_waitcnt lgkmcnt(2)
	v_lshlrev_b32_e32 v146, 16, v246
	v_and_b32_e32 v147, 0xffff0000, v246
	v_lshlrev_b32_e32 v148, 16, v247
	v_and_b32_e32 v149, 0xffff0000, v247
	v_pk_mul_f32 v[120:121], v[120:121], v[146:147]
	v_pk_mul_f32 v[122:123], v[122:123], v[148:149]
	v_lshlrev_b32_e32 v150, 16, v162
	v_and_b32_e32 v151, 0xffff0000, v162
	v_lshlrev_b32_e32 v152, 16, v163
	v_and_b32_e32 v153, 0xffff0000, v163
	v_pk_add_f32 v[120:121], v[120:121], v[150:151]
	v_pk_add_f32 v[122:123], v[122:123], v[152:153]
	v_cvt_pk_bf16_f32 v126, v120, v121
	v_cvt_pk_bf16_f32 v127, v122, v123
	s_waitcnt lgkmcnt(1)
	v_lshlrev_b32_e32 v146, 16, v248
	v_and_b32_e32 v147, 0xffff0000, v248
	v_lshlrev_b32_e32 v148, 16, v249
	v_and_b32_e32 v149, 0xffff0000, v249
	v_pk_mul_f32 v[116:117], v[116:117], v[146:147]
	v_pk_mul_f32 v[118:119], v[118:119], v[148:149]
	v_lshlrev_b32_e32 v150, 16, v164
	v_and_b32_e32 v151, 0xffff0000, v164
	v_lshlrev_b32_e32 v152, 16, v165
	v_and_b32_e32 v153, 0xffff0000, v165
	v_pk_add_f32 v[116:117], v[116:117], v[150:151]
	v_pk_add_f32 v[118:119], v[118:119], v[152:153]
	v_cvt_pk_bf16_f32 v116, v116, v117
	v_cvt_pk_bf16_f32 v117, v118, v119
	s_waitcnt lgkmcnt(0)
	v_lshlrev_b32_e32 v146, 16, v250
	v_and_b32_e32 v147, 0xffff0000, v250
	v_lshlrev_b32_e32 v148, 16, v251
	v_and_b32_e32 v149, 0xffff0000, v251
	v_pk_mul_f32 v[112:113], v[112:113], v[146:147]
	v_pk_mul_f32 v[114:115], v[114:115], v[148:149]
	v_lshlrev_b32_e32 v150, 16, v166
	v_and_b32_e32 v151, 0xffff0000, v166
	v_lshlrev_b32_e32 v152, 16, v167
	v_and_b32_e32 v153, 0xffff0000, v167
	v_pk_add_f32 v[112:113], v[112:113], v[150:151]
	v_pk_add_f32 v[114:115], v[114:115], v[152:153]
	v_cvt_pk_bf16_f32 v118, v112, v113
	v_cvt_pk_bf16_f32 v119, v114, v115
	ds_read_b64 v[244:245], v134 offset:8448
	ds_read_b64 v[246:247], v135 offset:8448
	ds_read_b64 v[248:249], v134 offset:8192
	ds_read_b64 v[250:251], v135 offset:8192
	s_waitcnt lgkmcnt(3)
	v_lshlrev_b32_e32 v146, 16, v244
	v_and_b32_e32 v147, 0xffff0000, v244
	v_lshlrev_b32_e32 v148, 16, v245
	v_and_b32_e32 v149, 0xffff0000, v245
	v_pk_mul_f32 v[108:109], v[108:109], v[146:147]
	v_pk_mul_f32 v[110:111], v[110:111], v[148:149]
	v_lshlrev_b32_e32 v150, 16, v168
	v_and_b32_e32 v151, 0xffff0000, v168
	v_lshlrev_b32_e32 v152, 16, v169
	v_and_b32_e32 v153, 0xffff0000, v169
	v_pk_add_f32 v[108:109], v[108:109], v[150:151]
	v_pk_add_f32 v[110:111], v[110:111], v[152:153]
	v_cvt_pk_bf16_f32 v108, v108, v109
	v_cvt_pk_bf16_f32 v109, v110, v111
	s_waitcnt lgkmcnt(2)
	v_lshlrev_b32_e32 v146, 16, v246
	v_and_b32_e32 v147, 0xffff0000, v246
	v_lshlrev_b32_e32 v148, 16, v247
	v_and_b32_e32 v149, 0xffff0000, v247
	v_pk_mul_f32 v[104:105], v[104:105], v[146:147]
	v_pk_mul_f32 v[106:107], v[106:107], v[148:149]
	v_lshlrev_b32_e32 v150, 16, v170
	v_and_b32_e32 v151, 0xffff0000, v170
	v_lshlrev_b32_e32 v152, 16, v171
	v_and_b32_e32 v153, 0xffff0000, v171
	v_pk_add_f32 v[104:105], v[104:105], v[150:151]
	v_pk_add_f32 v[106:107], v[106:107], v[152:153]
	v_cvt_pk_bf16_f32 v110, v104, v105
	v_cvt_pk_bf16_f32 v111, v106, v107
	s_waitcnt lgkmcnt(1)
; DEV u32x2 pk4(f32x4 v) { u32x2 r = {pk_bf16(v[0], v[1]), pk_bf16(v[2], v[3])}; return r; }
; DEV f32x4 unpk4(u32x2 u) { f32x4 r = {bf_lo(u[0]), bf_hi(u[0]), bf_lo(u[1]), bf_hi(u[1])}; return r; }
;   DEV void operator()(f32x4 (&acc)[2][2][4][2], int brow, int bcol, int wr, int wc, int fr, int fq) const {
;     ...
;     for (int ai = 0; ai < 2; ++ai)
; #pragma unroll
;       for (int m = 0; m < 4; ++m) {
;         const int rl = ai * 128 + wr * 64 + m * 16 + fr, tok = brow + rl;
; #pragma unroll
;         for (int bj = 0; bj < 2; ++bj)
; #pragma unroll
;           for (int n = 0; n < 2; ++n) {
;             const int cl = bj * 128 + wc * 32 + n * 16 + fq * 4, col = bcol + cl;
;             const int f = ((ai * 4 + m) * 2 + bj) * 2 + n;
;             const f32x4 g = unpk4(tile_get4(rl, cl));
;             f32x4 v = acc[ai][bj][m][n] * g;
;             if (step == 0) sp[(size_t)f * 512] = pk4(v);
;             else if (step == 1) sp[(size_t)f * 512] = pk4(unpk4(sp[(size_t)f * 512]) + v);
	v_lshlrev_b32_e32 v146, 16, v248
	v_and_b32_e32 v147, 0xffff0000, v248
	v_lshlrev_b32_e32 v148, 16, v249
	v_and_b32_e32 v149, 0xffff0000, v249
	v_pk_mul_f32 v[100:101], v[100:101], v[146:147]
	v_pk_mul_f32 v[102:103], v[102:103], v[148:149]
	v_lshlrev_b32_e32 v150, 16, v172
	v_and_b32_e32 v151, 0xffff0000, v172
	v_lshlrev_b32_e32 v152, 16, v173
	v_and_b32_e32 v153, 0xffff0000, v173
	v_pk_add_f32 v[100:101], v[100:101], v[150:151]
	v_pk_add_f32 v[102:103], v[102:103], v[152:153]
	v_cvt_pk_bf16_f32 v100, v100, v101
	v_cvt_pk_bf16_f32 v101, v102, v103
	s_waitcnt lgkmcnt(0)
	v_lshlrev_b32_e32 v146, 16, v250
	v_and_b32_e32 v147, 0xffff0000, v250
	v_lshlrev_b32_e32 v148, 16, v251
	v_and_b32_e32 v149, 0xffff0000, v251
	v_pk_mul_f32 v[96:97], v[96:97], v[146:147]
	v_pk_mul_f32 v[98:99], v[98:99], v[148:149]
	v_lshlrev_b32_e32 v150, 16, v174
	v_and_b32_e32 v151, 0xffff0000, v174
	v_lshlrev_b32_e32 v152, 16, v175
	v_and_b32_e32 v153, 0xffff0000, v175
	v_pk_add_f32 v[96:97], v[96:97], v[150:151]
	v_pk_add_f32 v[98:99], v[98:99], v[152:153]
	v_cvt_pk_bf16_f32 v102, v96, v97
	v_cvt_pk_bf16_f32 v103, v98, v99
	ds_read_b64 v[244:245], v134 offset:16384
	ds_read_b64 v[246:247], v135 offset:16384
	ds_read_b64 v[248:249], v134 offset:16640
	ds_read_b64 v[250:251], v135 offset:16640
	s_waitcnt lgkmcnt(3)
	v_lshlrev_b32_e32 v146, 16, v244
	v_and_b32_e32 v147, 0xffff0000, v244
	v_lshlrev_b32_e32 v148, 16, v245
	v_and_b32_e32 v149, 0xffff0000, v245
	v_pk_mul_f32 v[92:93], v[92:93], v[146:147]
	v_pk_mul_f32 v[94:95], v[94:95], v[148:149]
	v_lshlrev_b32_e32 v150, 16, v184
	v_and_b32_e32 v151, 0xffff0000, v184
	v_lshlrev_b32_e32 v152, 16, v185
	v_and_b32_e32 v153, 0xffff0000, v185
	v_pk_add_f32 v[92:93], v[92:93], v[150:151]
	v_pk_add_f32 v[94:95], v[94:95], v[152:153]
	v_cvt_pk_bf16_f32 v92, v92, v93
	v_cvt_pk_bf16_f32 v93, v94, v95
	s_waitcnt lgkmcnt(2)
	v_lshlrev_b32_e32 v146, 16, v246
	v_and_b32_e32 v147, 0xffff0000, v246
	v_lshlrev_b32_e32 v148, 16, v247
	v_and_b32_e32 v149, 0xffff0000, v247
	v_pk_mul_f32 v[88:89], v[88:89], v[146:147]
	v_pk_mul_f32 v[90:91], v[90:91], v[148:149]
	v_lshlrev_b32_e32 v150, 16, v186
	v_and_b32_e32 v151, 0xffff0000, v186
	v_lshlrev_b32_e32 v152, 16, v187
	v_and_b32_e32 v153, 0xffff0000, v187
	v_pk_add_f32 v[88:89], v[88:89], v[150:151]
	v_pk_add_f32 v[90:91], v[90:91], v[152:153]
	v_cvt_pk_bf16_f32 v94, v88, v89
	v_cvt_pk_bf16_f32 v95, v90, v91
	s_waitcnt lgkmcnt(1)
	v_lshlrev_b32_e32 v146, 16, v248
	v_and_b32_e32 v147, 0xffff0000, v248
	v_lshlrev_b32_e32 v148, 16, v249
	v_and_b32_e32 v149, 0xffff0000, v249
	v_pk_mul_f32 v[84:85], v[84:85], v[146:147]
	v_pk_mul_f32 v[86:87], v[86:87], v[148:149]
	v_lshlrev_b32_e32 v150, 16, v188
	v_and_b32_e32 v151, 0xffff0000, v188
	v_lshlrev_b32_e32 v152, 16, v189
	v_and_b32_e32 v153, 0xffff0000, v189
	v_pk_add_f32 v[84:85], v[84:85], v[150:151]
	v_pk_add_f32 v[86:87], v[86:87], v[152:153]
	v_cvt_pk_bf16_f32 v84, v84, v85
	v_cvt_pk_bf16_f32 v85, v86, v87
	s_waitcnt lgkmcnt(0)
	v_lshlrev_b32_e32 v146, 16, v250
	v_and_b32_e32 v147, 0xffff0000, v250
	v_lshlrev_b32_e32 v148, 16, v251
	v_and_b32_e32 v149, 0xffff0000, v251
	v_pk_mul_f32 v[80:81], v[80:81], v[146:147]
	v_pk_mul_f32 v[82:83], v[82:83], v[148:149]
	v_lshlrev_b32_e32 v150, 16, v190
	v_and_b32_e32 v151, 0xffff0000, v190
	v_lshlrev_b32_e32 v152, 16, v191
	v_and_b32_e32 v153, 0xffff0000, v191
	v_pk_add_f32 v[80:81], v[80:81], v[150:151]
	v_pk_add_f32 v[82:83], v[82:83], v[152:153]
	v_cvt_pk_bf16_f32 v86, v80, v81
	v_cvt_pk_bf16_f32 v87, v82, v83
	ds_read_b64 v[244:245], v134 offset:24832
	ds_read_b64 v[246:247], v135 offset:24832
	ds_read_b64 v[248:249], v134 offset:24576
	ds_read_b64 v[250:251], v135 offset:24576
	s_waitcnt lgkmcnt(3)
	v_lshlrev_b32_e32 v146, 16, v244
	v_and_b32_e32 v147, 0xffff0000, v244
	v_lshlrev_b32_e32 v148, 16, v245
	v_and_b32_e32 v149, 0xffff0000, v245
	v_pk_mul_f32 v[76:77], v[76:77], v[146:147]
	v_pk_mul_f32 v[78:79], v[78:79], v[148:149]
	v_lshlrev_b32_e32 v150, 16, v192
	v_and_b32_e32 v151, 0xffff0000, v192
	v_lshlrev_b32_e32 v152, 16, v193
	v_and_b32_e32 v153, 0xffff0000, v193
	v_pk_add_f32 v[76:77], v[76:77], v[150:151]
	v_pk_add_f32 v[78:79], v[78:79], v[152:153]
	v_cvt_pk_bf16_f32 v76, v76, v77
	v_cvt_pk_bf16_f32 v77, v78, v79
	s_waitcnt lgkmcnt(2)
	v_lshlrev_b32_e32 v146, 16, v246
	v_and_b32_e32 v147, 0xffff0000, v246
	v_lshlrev_b32_e32 v148, 16, v247
	v_and_b32_e32 v149, 0xffff0000, v247
	v_pk_mul_f32 v[72:73], v[72:73], v[146:147]
	v_pk_mul_f32 v[74:75], v[74:75], v[148:149]
	v_lshlrev_b32_e32 v150, 16, v194
	v_and_b32_e32 v151, 0xffff0000, v194
	v_lshlrev_b32_e32 v152, 16, v195
	v_and_b32_e32 v153, 0xffff0000, v195
	v_pk_add_f32 v[72:73], v[72:73], v[150:151]
	v_pk_add_f32 v[74:75], v[74:75], v[152:153]
	v_cvt_pk_bf16_f32 v78, v72, v73
	v_cvt_pk_bf16_f32 v79, v74, v75
	s_waitcnt lgkmcnt(1)
	v_lshlrev_b32_e32 v146, 16, v248
	v_and_b32_e32 v147, 0xffff0000, v248
	v_lshlrev_b32_e32 v148, 16, v249
	v_and_b32_e32 v149, 0xffff0000, v249
	v_pk_mul_f32 v[68:69], v[68:69], v[146:147]
	v_pk_mul_f32 v[70:71], v[70:71], v[148:149]
	v_lshlrev_b32_e32 v150, 16, v200
	v_and_b32_e32 v151, 0xffff0000, v200
	v_lshlrev_b32_e32 v152, 16, v201
	v_and_b32_e32 v153, 0xffff0000, v201
	v_pk_add_f32 v[68:69], v[68:69], v[150:151]
	v_pk_add_f32 v[70:71], v[70:71], v[152:153]
	v_cvt_pk_bf16_f32 v68, v68, v69
	v_cvt_pk_bf16_f32 v69, v70, v71
	s_waitcnt lgkmcnt(0)
; DEV u32x2 pk4(f32x4 v) { u32x2 r = {pk_bf16(v[0], v[1]), pk_bf16(v[2], v[3])}; return r; }
; DEV f32x4 unpk4(u32x2 u) { f32x4 r = {bf_lo(u[0]), bf_hi(u[0]), bf_lo(u[1]), bf_hi(u[1])}; return r; }
;   DEV void operator()(f32x4 (&acc)[2][2][4][2], int brow, int bcol, int wr, int wc, int fr, int fq) const {
;     ...
;     for (int ai = 0; ai < 2; ++ai)
; #pragma unroll
;       for (int m = 0; m < 4; ++m) {
;         const int rl = ai * 128 + wr * 64 + m * 16 + fr, tok = brow + rl;
; #pragma unroll
;         for (int bj = 0; bj < 2; ++bj)
; #pragma unroll
;           for (int n = 0; n < 2; ++n) {
;             const int cl = bj * 128 + wc * 32 + n * 16 + fq * 4, col = bcol + cl;
;             const int f = ((ai * 4 + m) * 2 + bj) * 2 + n;
;             const f32x4 g = unpk4(tile_get4(rl, cl));
;             f32x4 v = acc[ai][bj][m][n] * g;
;             if (step == 0) sp[(size_t)f * 512] = pk4(v);
;             else if (step == 1) sp[(size_t)f * 512] = pk4(unpk4(sp[(size_t)f * 512]) + v);
	v_lshlrev_b32_e32 v146, 16, v250
	v_and_b32_e32 v147, 0xffff0000, v250
	v_lshlrev_b32_e32 v148, 16, v251
	v_and_b32_e32 v149, 0xffff0000, v251
	v_pk_mul_f32 v[64:65], v[64:65], v[146:147]
	v_pk_mul_f32 v[66:67], v[66:67], v[148:149]
	v_lshlrev_b32_e32 v150, 16, v202
	v_and_b32_e32 v151, 0xffff0000, v202
	v_lshlrev_b32_e32 v152, 16, v203
	v_and_b32_e32 v153, 0xffff0000, v203
	v_pk_add_f32 v[64:65], v[64:65], v[150:151]
	v_pk_add_f32 v[66:67], v[66:67], v[152:153]
	v_cvt_pk_bf16_f32 v70, v64, v65
	v_cvt_pk_bf16_f32 v71, v66, v67
	ds_read_b64 v[244:245], v136
	ds_read_b64 v[246:247], v137
	ds_read_b64 v[248:249], v136 offset:256
	ds_read_b64 v[250:251], v137 offset:256
	s_waitcnt lgkmcnt(3)
	v_lshlrev_b32_e32 v146, 16, v244
	v_and_b32_e32 v147, 0xffff0000, v244
	v_lshlrev_b32_e32 v148, 16, v245
	v_and_b32_e32 v149, 0xffff0000, v245
	v_pk_mul_f32 v[60:61], v[60:61], v[146:147]
	v_pk_mul_f32 v[62:63], v[62:63], v[148:149]
	v_lshlrev_b32_e32 v150, 16, v204
	v_and_b32_e32 v151, 0xffff0000, v204
	v_lshlrev_b32_e32 v152, 16, v205
	v_and_b32_e32 v153, 0xffff0000, v205
	v_pk_add_f32 v[60:61], v[60:61], v[150:151]
	v_pk_add_f32 v[62:63], v[62:63], v[152:153]
	v_cvt_pk_bf16_f32 v60, v60, v61
	v_cvt_pk_bf16_f32 v61, v62, v63
	s_waitcnt lgkmcnt(2)
	v_lshlrev_b32_e32 v146, 16, v246
	v_and_b32_e32 v147, 0xffff0000, v246
	v_lshlrev_b32_e32 v148, 16, v247
	v_and_b32_e32 v149, 0xffff0000, v247
	v_pk_mul_f32 v[56:57], v[56:57], v[146:147]
	v_pk_mul_f32 v[58:59], v[58:59], v[148:149]
	v_lshlrev_b32_e32 v150, 16, v206
	v_and_b32_e32 v151, 0xffff0000, v206
	v_lshlrev_b32_e32 v152, 16, v207
	v_and_b32_e32 v153, 0xffff0000, v207
	v_pk_add_f32 v[56:57], v[56:57], v[150:151]
	v_pk_add_f32 v[58:59], v[58:59], v[152:153]
	v_cvt_pk_bf16_f32 v62, v56, v57
	v_cvt_pk_bf16_f32 v63, v58, v59
	s_waitcnt lgkmcnt(1)
	v_lshlrev_b32_e32 v146, 16, v248
	v_and_b32_e32 v147, 0xffff0000, v248
	v_lshlrev_b32_e32 v148, 16, v249
	v_and_b32_e32 v149, 0xffff0000, v249
	v_pk_mul_f32 v[52:53], v[52:53], v[146:147]
	v_pk_mul_f32 v[54:55], v[54:55], v[148:149]
	v_lshlrev_b32_e32 v150, 16, v208
	v_and_b32_e32 v151, 0xffff0000, v208
	v_lshlrev_b32_e32 v152, 16, v209
	v_and_b32_e32 v153, 0xffff0000, v209
	v_pk_add_f32 v[52:53], v[52:53], v[150:151]
	v_pk_add_f32 v[54:55], v[54:55], v[152:153]
	v_cvt_pk_bf16_f32 v52, v52, v53
	v_cvt_pk_bf16_f32 v53, v54, v55
	s_waitcnt lgkmcnt(0)
	v_lshlrev_b32_e32 v146, 16, v250
	v_and_b32_e32 v147, 0xffff0000, v250
	v_lshlrev_b32_e32 v148, 16, v251
	v_and_b32_e32 v149, 0xffff0000, v251
	v_pk_mul_f32 v[48:49], v[48:49], v[146:147]
	v_pk_mul_f32 v[50:51], v[50:51], v[148:149]
	v_lshlrev_b32_e32 v150, 16, v210
	v_and_b32_e32 v151, 0xffff0000, v210
	v_lshlrev_b32_e32 v152, 16, v211
	v_and_b32_e32 v153, 0xffff0000, v211
	v_pk_add_f32 v[48:49], v[48:49], v[150:151]
	v_pk_add_f32 v[50:51], v[50:51], v[152:153]
	v_cvt_pk_bf16_f32 v54, v48, v49
	v_cvt_pk_bf16_f32 v55, v50, v51
	ds_read_b64 v[244:245], v136 offset:8448
	ds_read_b64 v[246:247], v137 offset:8448
	ds_read_b64 v[248:249], v136 offset:8192
	ds_read_b64 v[250:251], v137 offset:8192
	s_waitcnt lgkmcnt(3)
	v_lshlrev_b32_e32 v146, 16, v244
	v_and_b32_e32 v147, 0xffff0000, v244
	v_lshlrev_b32_e32 v148, 16, v245
	v_and_b32_e32 v149, 0xffff0000, v245
	v_pk_mul_f32 v[44:45], v[44:45], v[146:147]
	v_pk_mul_f32 v[46:47], v[46:47], v[148:149]
	v_lshlrev_b32_e32 v150, 16, v212
	v_and_b32_e32 v151, 0xffff0000, v212
	v_lshlrev_b32_e32 v152, 16, v213
	v_and_b32_e32 v153, 0xffff0000, v213
	v_pk_add_f32 v[44:45], v[44:45], v[150:151]
	v_pk_add_f32 v[46:47], v[46:47], v[152:153]
	v_cvt_pk_bf16_f32 v44, v44, v45
	v_cvt_pk_bf16_f32 v45, v46, v47
	s_waitcnt lgkmcnt(2)
	v_lshlrev_b32_e32 v146, 16, v246
	v_and_b32_e32 v147, 0xffff0000, v246
	v_lshlrev_b32_e32 v148, 16, v247
	v_and_b32_e32 v149, 0xffff0000, v247
	v_pk_mul_f32 v[40:41], v[40:41], v[146:147]
	v_pk_mul_f32 v[42:43], v[42:43], v[148:149]
	v_lshlrev_b32_e32 v150, 16, v214
	v_and_b32_e32 v151, 0xffff0000, v214
	v_lshlrev_b32_e32 v152, 16, v215
	v_and_b32_e32 v153, 0xffff0000, v215
	v_pk_add_f32 v[40:41], v[40:41], v[150:151]
	v_pk_add_f32 v[42:43], v[42:43], v[152:153]
	v_cvt_pk_bf16_f32 v46, v40, v41
	v_cvt_pk_bf16_f32 v47, v42, v43
	s_waitcnt lgkmcnt(1)
	v_lshlrev_b32_e32 v146, 16, v248
	v_and_b32_e32 v147, 0xffff0000, v248
	v_lshlrev_b32_e32 v148, 16, v249
	v_and_b32_e32 v149, 0xffff0000, v249
	v_pk_mul_f32 v[36:37], v[36:37], v[146:147]
	v_pk_mul_f32 v[38:39], v[38:39], v[148:149]
	v_lshlrev_b32_e32 v150, 16, v224
	v_and_b32_e32 v151, 0xffff0000, v224
	v_lshlrev_b32_e32 v152, 16, v225
	v_and_b32_e32 v153, 0xffff0000, v225
	v_pk_add_f32 v[36:37], v[36:37], v[150:151]
	v_pk_add_f32 v[38:39], v[38:39], v[152:153]
	v_cvt_pk_bf16_f32 v36, v36, v37
	v_cvt_pk_bf16_f32 v37, v38, v39
	s_waitcnt lgkmcnt(0)
	v_lshlrev_b32_e32 v146, 16, v250
	v_and_b32_e32 v147, 0xffff0000, v250
	v_lshlrev_b32_e32 v148, 16, v251
	v_and_b32_e32 v149, 0xffff0000, v251
	v_pk_mul_f32 v[32:33], v[32:33], v[146:147]
	v_pk_mul_f32 v[34:35], v[34:35], v[148:149]
	v_lshlrev_b32_e32 v150, 16, v226
	v_and_b32_e32 v151, 0xffff0000, v226
	v_lshlrev_b32_e32 v152, 16, v227
	v_and_b32_e32 v153, 0xffff0000, v227
	v_pk_add_f32 v[32:33], v[32:33], v[150:151]
	v_pk_add_f32 v[34:35], v[34:35], v[152:153]
	v_cvt_pk_bf16_f32 v38, v32, v33
	v_cvt_pk_bf16_f32 v39, v34, v35
	ds_read_b64 v[244:245], v136 offset:16384
	ds_read_b64 v[246:247], v137 offset:16384
	ds_read_b64 v[248:249], v136 offset:16640
	ds_read_b64 v[250:251], v137 offset:16640
	s_waitcnt lgkmcnt(3)
; DEV u32x2 pk4(f32x4 v) { u32x2 r = {pk_bf16(v[0], v[1]), pk_bf16(v[2], v[3])}; return r; }
; DEV f32x4 unpk4(u32x2 u) { f32x4 r = {bf_lo(u[0]), bf_hi(u[0]), bf_lo(u[1]), bf_hi(u[1])}; return r; }
;   DEV void operator()(f32x4 (&acc)[2][2][4][2], int brow, int bcol, int wr, int wc, int fr, int fq) const {
;     ...
;     for (int ai = 0; ai < 2; ++ai)
; #pragma unroll
;       for (int m = 0; m < 4; ++m) {
;         const int rl = ai * 128 + wr * 64 + m * 16 + fr, tok = brow + rl;
; #pragma unroll
;         for (int bj = 0; bj < 2; ++bj)
; #pragma unroll
;           for (int n = 0; n < 2; ++n) {
;             const int cl = bj * 128 + wc * 32 + n * 16 + fq * 4, col = bcol + cl;
;             const int f = ((ai * 4 + m) * 2 + bj) * 2 + n;
;             const f32x4 g = unpk4(tile_get4(rl, cl));
;             f32x4 v = acc[ai][bj][m][n] * g;
;             if (step == 0) sp[(size_t)f * 512] = pk4(v);
;             else if (step == 1) sp[(size_t)f * 512] = pk4(unpk4(sp[(size_t)f * 512]) + v);
	v_lshlrev_b32_e32 v146, 16, v244
	v_and_b32_e32 v147, 0xffff0000, v244
	v_lshlrev_b32_e32 v148, 16, v245
	v_and_b32_e32 v149, 0xffff0000, v245
	v_pk_mul_f32 v[28:29], v[28:29], v[146:147]
	v_pk_mul_f32 v[30:31], v[30:31], v[148:149]
	v_lshlrev_b32_e32 v150, 16, v228
	v_and_b32_e32 v151, 0xffff0000, v228
	v_lshlrev_b32_e32 v152, 16, v229
	v_and_b32_e32 v153, 0xffff0000, v229
	v_pk_add_f32 v[28:29], v[28:29], v[150:151]
	v_pk_add_f32 v[30:31], v[30:31], v[152:153]
	v_cvt_pk_bf16_f32 v28, v28, v29
	v_cvt_pk_bf16_f32 v29, v30, v31
	s_waitcnt lgkmcnt(2)
	v_lshlrev_b32_e32 v146, 16, v246
	v_and_b32_e32 v147, 0xffff0000, v246
	v_lshlrev_b32_e32 v148, 16, v247
	v_and_b32_e32 v149, 0xffff0000, v247
	v_pk_mul_f32 v[24:25], v[24:25], v[146:147]
	v_pk_mul_f32 v[26:27], v[26:27], v[148:149]
	v_lshlrev_b32_e32 v150, 16, v230
	v_and_b32_e32 v151, 0xffff0000, v230
	v_lshlrev_b32_e32 v152, 16, v231
	v_and_b32_e32 v153, 0xffff0000, v231
	v_pk_add_f32 v[24:25], v[24:25], v[150:151]
	v_pk_add_f32 v[26:27], v[26:27], v[152:153]
	v_cvt_pk_bf16_f32 v30, v24, v25
	v_cvt_pk_bf16_f32 v31, v26, v27
	s_waitcnt lgkmcnt(1)
	v_lshlrev_b32_e32 v146, 16, v248
	v_and_b32_e32 v147, 0xffff0000, v248
	v_lshlrev_b32_e32 v148, 16, v249
	v_and_b32_e32 v149, 0xffff0000, v249
	v_pk_mul_f32 v[20:21], v[20:21], v[146:147]
	v_pk_mul_f32 v[22:23], v[22:23], v[148:149]
	v_lshlrev_b32_e32 v150, 16, v232
	v_and_b32_e32 v151, 0xffff0000, v232
	v_lshlrev_b32_e32 v152, 16, v233
	v_and_b32_e32 v153, 0xffff0000, v233
	v_pk_add_f32 v[20:21], v[20:21], v[150:151]
	v_pk_add_f32 v[22:23], v[22:23], v[152:153]
	v_cvt_pk_bf16_f32 v20, v20, v21
	v_cvt_pk_bf16_f32 v21, v22, v23
	s_waitcnt lgkmcnt(0)
	v_lshlrev_b32_e32 v146, 16, v250
	v_and_b32_e32 v147, 0xffff0000, v250
	v_lshlrev_b32_e32 v148, 16, v251
	v_and_b32_e32 v149, 0xffff0000, v251
	v_pk_mul_f32 v[16:17], v[16:17], v[146:147]
	v_pk_mul_f32 v[18:19], v[18:19], v[148:149]
	v_lshlrev_b32_e32 v150, 16, v234
	v_and_b32_e32 v151, 0xffff0000, v234
	v_lshlrev_b32_e32 v152, 16, v235
	v_and_b32_e32 v153, 0xffff0000, v235
	v_pk_add_f32 v[16:17], v[16:17], v[150:151]
	v_pk_add_f32 v[18:19], v[18:19], v[152:153]
	v_cvt_pk_bf16_f32 v22, v16, v17
	v_cvt_pk_bf16_f32 v23, v18, v19
	ds_read_b64 v[244:245], v136 offset:24832
	ds_read_b64 v[246:247], v137 offset:24832
	ds_read_b64 v[248:249], v136 offset:24576
	ds_read_b64 v[250:251], v137 offset:24576
	s_waitcnt lgkmcnt(3)
	v_lshlrev_b32_e32 v146, 16, v244
	v_and_b32_e32 v147, 0xffff0000, v244
	v_lshlrev_b32_e32 v148, 16, v245
	v_and_b32_e32 v149, 0xffff0000, v245
	v_pk_mul_f32 v[12:13], v[12:13], v[146:147]
	v_pk_mul_f32 v[14:15], v[14:15], v[148:149]
	v_lshlrev_b32_e32 v150, 16, v236
	v_and_b32_e32 v151, 0xffff0000, v236
	v_lshlrev_b32_e32 v152, 16, v237
	v_and_b32_e32 v153, 0xffff0000, v237
	v_pk_add_f32 v[12:13], v[12:13], v[150:151]
	v_pk_add_f32 v[14:15], v[14:15], v[152:153]
	v_cvt_pk_bf16_f32 v12, v12, v13
	v_cvt_pk_bf16_f32 v13, v14, v15
	s_waitcnt lgkmcnt(2)
	v_lshlrev_b32_e32 v146, 16, v246
	v_and_b32_e32 v147, 0xffff0000, v246
	v_lshlrev_b32_e32 v148, 16, v247
	v_and_b32_e32 v149, 0xffff0000, v247
	v_pk_mul_f32 v[8:9], v[8:9], v[146:147]
	v_pk_mul_f32 v[10:11], v[10:11], v[148:149]
	v_lshlrev_b32_e32 v150, 16, v238
	v_and_b32_e32 v151, 0xffff0000, v238
	v_lshlrev_b32_e32 v152, 16, v239
	v_and_b32_e32 v153, 0xffff0000, v239
	v_pk_add_f32 v[8:9], v[8:9], v[150:151]
	v_pk_add_f32 v[10:11], v[10:11], v[152:153]
	v_cvt_pk_bf16_f32 v14, v8, v9
	v_cvt_pk_bf16_f32 v15, v10, v11
	s_waitcnt lgkmcnt(1)
	v_lshlrev_b32_e32 v146, 16, v248
	v_and_b32_e32 v147, 0xffff0000, v248
	v_lshlrev_b32_e32 v148, 16, v249
	v_and_b32_e32 v149, 0xffff0000, v249
	v_pk_mul_f32 v[4:5], v[4:5], v[146:147]
	v_pk_mul_f32 v[6:7], v[6:7], v[148:149]
	v_lshlrev_b32_e32 v150, 16, v240
	v_and_b32_e32 v151, 0xffff0000, v240
	v_lshlrev_b32_e32 v152, 16, v241
	v_and_b32_e32 v153, 0xffff0000, v241
	v_pk_add_f32 v[4:5], v[4:5], v[150:151]
	v_pk_add_f32 v[6:7], v[6:7], v[152:153]
	v_cvt_pk_bf16_f32 v4, v4, v5
	v_cvt_pk_bf16_f32 v5, v6, v7
	s_waitcnt lgkmcnt(0)
	v_lshlrev_b32_e32 v146, 16, v250
	v_and_b32_e32 v147, 0xffff0000, v250
	v_lshlrev_b32_e32 v148, 16, v251
	v_and_b32_e32 v149, 0xffff0000, v251
	v_pk_mul_f32 v[0:1], v[0:1], v[146:147]
	v_pk_mul_f32 v[2:3], v[2:3], v[148:149]
	v_lshlrev_b32_e32 v150, 16, v242
	v_and_b32_e32 v151, 0xffff0000, v242
	v_lshlrev_b32_e32 v152, 16, v243
	v_and_b32_e32 v153, 0xffff0000, v243
	v_pk_add_f32 v[0:1], v[0:1], v[150:151]
	v_pk_add_f32 v[2:3], v[2:3], v[152:153]
	v_cvt_pk_bf16_f32 v6, v0, v1
	v_cvt_pk_bf16_f32 v7, v2, v3
	v_lshlrev_b32_e32 v141, 4, v140
	global_store_dwordx4 v141, v[124:127], s[20:21]
	v_add_u32_e32 v141, 0x2000, v141
	global_store_dwordx4 v141, v[116:119], s[20:21]
	v_add_u32_e32 v141, 0x2000, v141
	global_store_dwordx4 v141, v[108:111], s[20:21]
	v_add_u32_e32 v141, 0x2000, v141
	global_store_dwordx4 v141, v[100:103], s[20:21]
	v_add_u32_e32 v141, 0x2000, v141
	global_store_dwordx4 v141, v[92:95], s[20:21]
	v_add_u32_e32 v141, 0x2000, v141
	global_store_dwordx4 v141, v[84:87], s[20:21]
	v_add_u32_e32 v141, 0x2000, v141
	global_store_dwordx4 v141, v[76:79], s[20:21]
	v_add_u32_e32 v141, 0x2000, v141
	global_store_dwordx4 v141, v[68:71], s[20:21]
	v_add_u32_e32 v141, 0x2000, v141
	global_store_dwordx4 v141, v[60:63], s[20:21]
	v_add_u32_e32 v141, 0x2000, v141
	global_store_dwordx4 v141, v[52:55], s[20:21]
	v_add_u32_e32 v141, 0x2000, v141
	global_store_dwordx4 v141, v[44:47], s[20:21]
	v_add_u32_e32 v141, 0x2000, v141
	global_store_dwordx4 v141, v[36:39], s[20:21]
	v_add_u32_e32 v141, 0x2000, v141
	global_store_dwordx4 v141, v[28:31], s[20:21]
	v_add_u32_e32 v141, 0x2000, v141
	global_store_dwordx4 v141, v[20:23], s[20:21]
	v_add_u32_e32 v141, 0x2000, v141
	global_store_dwordx4 v141, v[12:15], s[20:21]
	v_add_u32_e32 v141, 0x2000, v141
	global_store_dwordx4 v141, v[4:7], s[20:21]
	s_branch .LBB0_1272
; DEV u32x2 pk4(f32x4 v) { u32x2 r = {pk_bf16(v[0], v[1]), pk_bf16(v[2], v[3])}; return r; }
; DEV f32x4 unpk4(u32x2 u) { f32x4 r = {bf_lo(u[0]), bf_hi(u[0]), bf_lo(u[1]), bf_hi(u[1])}; return r; }
;   DEV void operator()(f32x4 (&acc)[2][2][4][2], int brow, int bcol, int wr, int wc, int fr, int fq) const {
;     ...
;     for (int ai = 0; ai < 2; ++ai)
; #pragma unroll
;       for (int m = 0; m < 4; ++m) {
;         const int rl = ai * 128 + wr * 64 + m * 16 + fr, tok = brow + rl;
; #pragma unroll
;         for (int bj = 0; bj < 2; ++bj)
; #pragma unroll
;           for (int n = 0; n < 2; ++n) {
;             const int cl = bj * 128 + wc * 32 + n * 16 + fq * 4, col = bcol + cl;
;             const int f = ((ai * 4 + m) * 2 + bj) * 2 + n;
;             const f32x4 g = unpk4(tile_get4(rl, cl));
;             f32x4 v = acc[ai][bj][m][n] * g;
;             if (step == 0) sp[(size_t)f * 512] = pk4(v);
;             else if (step == 1) sp[(size_t)f * 512] = pk4(unpk4(sp[(size_t)f * 512]) + v);
;             else tile_put4(rl, cl, pk4(unpk4(sp[(size_t)f * 512]) + v));
.Lp3l_step2:
	ds_read_b64 v[244:245], v134
	ds_read_b64 v[246:247], v135
	ds_read_b64 v[248:249], v134 offset:256
	ds_read_b64 v[250:251], v135 offset:256
	s_waitcnt lgkmcnt(3)
	v_lshlrev_b32_e32 v146, 16, v244
	v_and_b32_e32 v147, 0xffff0000, v244
	v_lshlrev_b32_e32 v148, 16, v245
	v_and_b32_e32 v149, 0xffff0000, v245
	v_pk_mul_f32 v[124:125], v[124:125], v[146:147]
	v_pk_mul_f32 v[126:127], v[126:127], v[148:149]
	v_lshlrev_b32_e32 v150, 16, v160
	v_and_b32_e32 v151, 0xffff0000, v160
	v_lshlrev_b32_e32 v152, 16, v161
	v_and_b32_e32 v153, 0xffff0000, v161
	v_pk_add_f32 v[124:125], v[124:125], v[150:151]
	v_pk_add_f32 v[126:127], v[126:127], v[152:153]
	v_cvt_pk_bf16_f32 v124, v124, v125
	v_cvt_pk_bf16_f32 v125, v126, v127
	ds_write_b64 v134, v[124:125]
	s_waitcnt lgkmcnt(2)
	v_lshlrev_b32_e32 v146, 16, v246
	v_and_b32_e32 v147, 0xffff0000, v246
	v_lshlrev_b32_e32 v148, 16, v247
	v_and_b32_e32 v149, 0xffff0000, v247
	v_pk_mul_f32 v[120:121], v[120:121], v[146:147]
	v_pk_mul_f32 v[122:123], v[122:123], v[148:149]
	v_lshlrev_b32_e32 v150, 16, v162
	v_and_b32_e32 v151, 0xffff0000, v162
	v_lshlrev_b32_e32 v152, 16, v163
	v_and_b32_e32 v153, 0xffff0000, v163
	v_pk_add_f32 v[120:121], v[120:121], v[150:151]
	v_pk_add_f32 v[122:123], v[122:123], v[152:153]
	v_cvt_pk_bf16_f32 v126, v120, v121
	v_cvt_pk_bf16_f32 v127, v122, v123
	ds_write_b64 v135, v[126:127]
	s_waitcnt lgkmcnt(1)
	v_lshlrev_b32_e32 v146, 16, v248
	v_and_b32_e32 v147, 0xffff0000, v248
	v_lshlrev_b32_e32 v148, 16, v249
	v_and_b32_e32 v149, 0xffff0000, v249
	v_pk_mul_f32 v[116:117], v[116:117], v[146:147]
	v_pk_mul_f32 v[118:119], v[118:119], v[148:149]
	v_lshlrev_b32_e32 v150, 16, v164
	v_and_b32_e32 v151, 0xffff0000, v164
	v_lshlrev_b32_e32 v152, 16, v165
	v_and_b32_e32 v153, 0xffff0000, v165
	v_pk_add_f32 v[116:117], v[116:117], v[150:151]
	v_pk_add_f32 v[118:119], v[118:119], v[152:153]
	v_cvt_pk_bf16_f32 v116, v116, v117
	v_cvt_pk_bf16_f32 v117, v118, v119
	ds_write_b64 v134, v[116:117] offset:256
	s_waitcnt lgkmcnt(0)
	v_lshlrev_b32_e32 v146, 16, v250
	v_and_b32_e32 v147, 0xffff0000, v250
	v_lshlrev_b32_e32 v148, 16, v251
	v_and_b32_e32 v149, 0xffff0000, v251
	v_pk_mul_f32 v[112:113], v[112:113], v[146:147]
	v_pk_mul_f32 v[114:115], v[114:115], v[148:149]
	v_lshlrev_b32_e32 v150, 16, v166
	v_and_b32_e32 v151, 0xffff0000, v166
	v_lshlrev_b32_e32 v152, 16, v167
	v_and_b32_e32 v153, 0xffff0000, v167
	v_pk_add_f32 v[112:113], v[112:113], v[150:151]
	v_pk_add_f32 v[114:115], v[114:115], v[152:153]
	v_cvt_pk_bf16_f32 v118, v112, v113
	v_cvt_pk_bf16_f32 v119, v114, v115
	ds_write_b64 v135, v[118:119] offset:256
	ds_read_b64 v[244:245], v134 offset:8448
	ds_read_b64 v[246:247], v135 offset:8448
	ds_read_b64 v[248:249], v134 offset:8192
	ds_read_b64 v[250:251], v135 offset:8192
	s_waitcnt lgkmcnt(3)
	v_lshlrev_b32_e32 v146, 16, v244
	v_and_b32_e32 v147, 0xffff0000, v244
	v_lshlrev_b32_e32 v148, 16, v245
	v_and_b32_e32 v149, 0xffff0000, v245
	v_pk_mul_f32 v[108:109], v[108:109], v[146:147]
	v_pk_mul_f32 v[110:111], v[110:111], v[148:149]
	v_lshlrev_b32_e32 v150, 16, v168
	v_and_b32_e32 v151, 0xffff0000, v168
	v_lshlrev_b32_e32 v152, 16, v169
	v_and_b32_e32 v153, 0xffff0000, v169
	v_pk_add_f32 v[108:109], v[108:109], v[150:151]
	v_pk_add_f32 v[110:111], v[110:111], v[152:153]
	v_cvt_pk_bf16_f32 v108, v108, v109
	v_cvt_pk_bf16_f32 v109, v110, v111
	ds_write_b64 v134, v[108:109] offset:8448
	s_waitcnt lgkmcnt(2)
	v_lshlrev_b32_e32 v146, 16, v246
	v_and_b32_e32 v147, 0xffff0000, v246
	v_lshlrev_b32_e32 v148, 16, v247
	v_and_b32_e32 v149, 0xffff0000, v247
	v_pk_mul_f32 v[104:105], v[104:105], v[146:147]
	v_pk_mul_f32 v[106:107], v[106:107], v[148:149]
	v_lshlrev_b32_e32 v150, 16, v170
	v_and_b32_e32 v151, 0xffff0000, v170
	v_lshlrev_b32_e32 v152, 16, v171
	v_and_b32_e32 v153, 0xffff0000, v171
	v_pk_add_f32 v[104:105], v[104:105], v[150:151]
	v_pk_add_f32 v[106:107], v[106:107], v[152:153]
	v_cvt_pk_bf16_f32 v110, v104, v105
	v_cvt_pk_bf16_f32 v111, v106, v107
	ds_write_b64 v135, v[110:111] offset:8448
	s_waitcnt lgkmcnt(1)
	v_lshlrev_b32_e32 v146, 16, v248
	v_and_b32_e32 v147, 0xffff0000, v248
	v_lshlrev_b32_e32 v148, 16, v249
	v_and_b32_e32 v149, 0xffff0000, v249
	v_pk_mul_f32 v[100:101], v[100:101], v[146:147]
	v_pk_mul_f32 v[102:103], v[102:103], v[148:149]
	v_lshlrev_b32_e32 v150, 16, v172
	v_and_b32_e32 v151, 0xffff0000, v172
	v_lshlrev_b32_e32 v152, 16, v173
	v_and_b32_e32 v153, 0xffff0000, v173
	v_pk_add_f32 v[100:101], v[100:101], v[150:151]
	v_pk_add_f32 v[102:103], v[102:103], v[152:153]
	v_cvt_pk_bf16_f32 v100, v100, v101
	v_cvt_pk_bf16_f32 v101, v102, v103
	ds_write_b64 v134, v[100:101] offset:8192
	s_waitcnt lgkmcnt(0)
	v_lshlrev_b32_e32 v146, 16, v250
	v_and_b32_e32 v147, 0xffff0000, v250
	v_lshlrev_b32_e32 v148, 16, v251
	v_and_b32_e32 v149, 0xffff0000, v251
	v_pk_mul_f32 v[96:97], v[96:97], v[146:147]
	v_pk_mul_f32 v[98:99], v[98:99], v[148:149]
	v_lshlrev_b32_e32 v150, 16, v174
	v_and_b32_e32 v151, 0xffff0000, v174
	v_lshlrev_b32_e32 v152, 16, v175
	v_and_b32_e32 v153, 0xffff0000, v175
	v_pk_add_f32 v[96:97], v[96:97], v[150:151]
	v_pk_add_f32 v[98:99], v[98:99], v[152:153]
	v_cvt_pk_bf16_f32 v102, v96, v97
	v_cvt_pk_bf16_f32 v103, v98, v99
	ds_write_b64 v135, v[102:103] offset:8192
	ds_read_b64 v[244:245], v134 offset:16384
	ds_read_b64 v[246:247], v135 offset:16384
	ds_read_b64 v[248:249], v134 offset:16640
	ds_read_b64 v[250:251], v135 offset:16640
	s_waitcnt lgkmcnt(3)
; DEV u32x2 pk4(f32x4 v) { u32x2 r = {pk_bf16(v[0], v[1]), pk_bf16(v[2], v[3])}; return r; }
; DEV f32x4 unpk4(u32x2 u) { f32x4 r = {bf_lo(u[0]), bf_hi(u[0]), bf_lo(u[1]), bf_hi(u[1])}; return r; }
;   DEV void operator()(f32x4 (&acc)[2][2][4][2], int brow, int bcol, int wr, int wc, int fr, int fq) const {
;     ...
;     for (int ai = 0; ai < 2; ++ai)
; #pragma unroll
;       for (int m = 0; m < 4; ++m) {
;         const int rl = ai * 128 + wr * 64 + m * 16 + fr, tok = brow + rl;
; #pragma unroll
;         for (int bj = 0; bj < 2; ++bj)
; #pragma unroll
;           for (int n = 0; n < 2; ++n) {
;             const int cl = bj * 128 + wc * 32 + n * 16 + fq * 4, col = bcol + cl;
;             const int f = ((ai * 4 + m) * 2 + bj) * 2 + n;
;             const f32x4 g = unpk4(tile_get4(rl, cl));
;             f32x4 v = acc[ai][bj][m][n] * g;
;             if (step == 0) sp[(size_t)f * 512] = pk4(v);
;             else if (step == 1) sp[(size_t)f * 512] = pk4(unpk4(sp[(size_t)f * 512]) + v);
;             else tile_put4(rl, cl, pk4(unpk4(sp[(size_t)f * 512]) + v));
	v_lshlrev_b32_e32 v146, 16, v244
	v_and_b32_e32 v147, 0xffff0000, v244
	v_lshlrev_b32_e32 v148, 16, v245
	v_and_b32_e32 v149, 0xffff0000, v245
	v_pk_mul_f32 v[92:93], v[92:93], v[146:147]
	v_pk_mul_f32 v[94:95], v[94:95], v[148:149]
	v_lshlrev_b32_e32 v150, 16, v184
	v_and_b32_e32 v151, 0xffff0000, v184
	v_lshlrev_b32_e32 v152, 16, v185
	v_and_b32_e32 v153, 0xffff0000, v185
	v_pk_add_f32 v[92:93], v[92:93], v[150:151]
	v_pk_add_f32 v[94:95], v[94:95], v[152:153]
	v_cvt_pk_bf16_f32 v92, v92, v93
	v_cvt_pk_bf16_f32 v93, v94, v95
	ds_write_b64 v134, v[92:93] offset:16384
	s_waitcnt lgkmcnt(2)
	v_lshlrev_b32_e32 v146, 16, v246
	v_and_b32_e32 v147, 0xffff0000, v246
	v_lshlrev_b32_e32 v148, 16, v247
	v_and_b32_e32 v149, 0xffff0000, v247
	v_pk_mul_f32 v[88:89], v[88:89], v[146:147]
	v_pk_mul_f32 v[90:91], v[90:91], v[148:149]
	v_lshlrev_b32_e32 v150, 16, v186
	v_and_b32_e32 v151, 0xffff0000, v186
	v_lshlrev_b32_e32 v152, 16, v187
	v_and_b32_e32 v153, 0xffff0000, v187
	v_pk_add_f32 v[88:89], v[88:89], v[150:151]
	v_pk_add_f32 v[90:91], v[90:91], v[152:153]
	v_cvt_pk_bf16_f32 v94, v88, v89
	v_cvt_pk_bf16_f32 v95, v90, v91
	ds_write_b64 v135, v[94:95] offset:16384
	s_waitcnt lgkmcnt(1)
	v_lshlrev_b32_e32 v146, 16, v248
	v_and_b32_e32 v147, 0xffff0000, v248
	v_lshlrev_b32_e32 v148, 16, v249
	v_and_b32_e32 v149, 0xffff0000, v249
	v_pk_mul_f32 v[84:85], v[84:85], v[146:147]
	v_pk_mul_f32 v[86:87], v[86:87], v[148:149]
	v_lshlrev_b32_e32 v150, 16, v188
	v_and_b32_e32 v151, 0xffff0000, v188
	v_lshlrev_b32_e32 v152, 16, v189
	v_and_b32_e32 v153, 0xffff0000, v189
	v_pk_add_f32 v[84:85], v[84:85], v[150:151]
	v_pk_add_f32 v[86:87], v[86:87], v[152:153]
	v_cvt_pk_bf16_f32 v84, v84, v85
	v_cvt_pk_bf16_f32 v85, v86, v87
	ds_write_b64 v134, v[84:85] offset:16640
	s_waitcnt lgkmcnt(0)
	v_lshlrev_b32_e32 v146, 16, v250
	v_and_b32_e32 v147, 0xffff0000, v250
	v_lshlrev_b32_e32 v148, 16, v251
	v_and_b32_e32 v149, 0xffff0000, v251
	v_pk_mul_f32 v[80:81], v[80:81], v[146:147]
	v_pk_mul_f32 v[82:83], v[82:83], v[148:149]
	v_lshlrev_b32_e32 v150, 16, v190
	v_and_b32_e32 v151, 0xffff0000, v190
	v_lshlrev_b32_e32 v152, 16, v191
	v_and_b32_e32 v153, 0xffff0000, v191
	v_pk_add_f32 v[80:81], v[80:81], v[150:151]
	v_pk_add_f32 v[82:83], v[82:83], v[152:153]
	v_cvt_pk_bf16_f32 v86, v80, v81
	v_cvt_pk_bf16_f32 v87, v82, v83
	ds_write_b64 v135, v[86:87] offset:16640
	ds_read_b64 v[244:245], v134 offset:24832
	ds_read_b64 v[246:247], v135 offset:24832
	ds_read_b64 v[248:249], v134 offset:24576
	ds_read_b64 v[250:251], v135 offset:24576
	s_waitcnt lgkmcnt(3)
	v_lshlrev_b32_e32 v146, 16, v244
	v_and_b32_e32 v147, 0xffff0000, v244
	v_lshlrev_b32_e32 v148, 16, v245
	v_and_b32_e32 v149, 0xffff0000, v245
	v_pk_mul_f32 v[76:77], v[76:77], v[146:147]
	v_pk_mul_f32 v[78:79], v[78:79], v[148:149]
	v_lshlrev_b32_e32 v150, 16, v192
	v_and_b32_e32 v151, 0xffff0000, v192
	v_lshlrev_b32_e32 v152, 16, v193
	v_and_b32_e32 v153, 0xffff0000, v193
	v_pk_add_f32 v[76:77], v[76:77], v[150:151]
	v_pk_add_f32 v[78:79], v[78:79], v[152:153]
	v_cvt_pk_bf16_f32 v76, v76, v77
	v_cvt_pk_bf16_f32 v77, v78, v79
	ds_write_b64 v134, v[76:77] offset:24832
	s_waitcnt lgkmcnt(2)
	v_lshlrev_b32_e32 v146, 16, v246
	v_and_b32_e32 v147, 0xffff0000, v246
	v_lshlrev_b32_e32 v148, 16, v247
	v_and_b32_e32 v149, 0xffff0000, v247
	v_pk_mul_f32 v[72:73], v[72:73], v[146:147]
	v_pk_mul_f32 v[74:75], v[74:75], v[148:149]
	v_lshlrev_b32_e32 v150, 16, v194
	v_and_b32_e32 v151, 0xffff0000, v194
	v_lshlrev_b32_e32 v152, 16, v195
	v_and_b32_e32 v153, 0xffff0000, v195
	v_pk_add_f32 v[72:73], v[72:73], v[150:151]
	v_pk_add_f32 v[74:75], v[74:75], v[152:153]
	v_cvt_pk_bf16_f32 v78, v72, v73
	v_cvt_pk_bf16_f32 v79, v74, v75
	ds_write_b64 v135, v[78:79] offset:24832
	s_waitcnt lgkmcnt(1)
	v_lshlrev_b32_e32 v146, 16, v248
	v_and_b32_e32 v147, 0xffff0000, v248
	v_lshlrev_b32_e32 v148, 16, v249
	v_and_b32_e32 v149, 0xffff0000, v249
	v_pk_mul_f32 v[68:69], v[68:69], v[146:147]
	v_pk_mul_f32 v[70:71], v[70:71], v[148:149]
	v_lshlrev_b32_e32 v150, 16, v200
	v_and_b32_e32 v151, 0xffff0000, v200
	v_lshlrev_b32_e32 v152, 16, v201
	v_and_b32_e32 v153, 0xffff0000, v201
	v_pk_add_f32 v[68:69], v[68:69], v[150:151]
	v_pk_add_f32 v[70:71], v[70:71], v[152:153]
	v_cvt_pk_bf16_f32 v68, v68, v69
	v_cvt_pk_bf16_f32 v69, v70, v71
	ds_write_b64 v134, v[68:69] offset:24576
	s_waitcnt lgkmcnt(0)
	v_lshlrev_b32_e32 v146, 16, v250
	v_and_b32_e32 v147, 0xffff0000, v250
	v_lshlrev_b32_e32 v148, 16, v251
	v_and_b32_e32 v149, 0xffff0000, v251
	v_pk_mul_f32 v[64:65], v[64:65], v[146:147]
	v_pk_mul_f32 v[66:67], v[66:67], v[148:149]
	v_lshlrev_b32_e32 v150, 16, v202
	v_and_b32_e32 v151, 0xffff0000, v202
	v_lshlrev_b32_e32 v152, 16, v203
	v_and_b32_e32 v153, 0xffff0000, v203
	v_pk_add_f32 v[64:65], v[64:65], v[150:151]
	v_pk_add_f32 v[66:67], v[66:67], v[152:153]
	v_cvt_pk_bf16_f32 v70, v64, v65
	v_cvt_pk_bf16_f32 v71, v66, v67
	ds_write_b64 v135, v[70:71] offset:24576
	ds_read_b64 v[244:245], v136
	ds_read_b64 v[246:247], v137
	ds_read_b64 v[248:249], v136 offset:256
	ds_read_b64 v[250:251], v137 offset:256
	s_waitcnt lgkmcnt(3)
	v_lshlrev_b32_e32 v146, 16, v244
	v_and_b32_e32 v147, 0xffff0000, v244
	v_lshlrev_b32_e32 v148, 16, v245
	v_and_b32_e32 v149, 0xffff0000, v245
	v_pk_mul_f32 v[60:61], v[60:61], v[146:147]
	v_pk_mul_f32 v[62:63], v[62:63], v[148:149]
	v_lshlrev_b32_e32 v150, 16, v204
	v_and_b32_e32 v151, 0xffff0000, v204
	v_lshlrev_b32_e32 v152, 16, v205
	v_and_b32_e32 v153, 0xffff0000, v205
	v_pk_add_f32 v[60:61], v[60:61], v[150:151]
	v_pk_add_f32 v[62:63], v[62:63], v[152:153]
	v_cvt_pk_bf16_f32 v60, v60, v61
	v_cvt_pk_bf16_f32 v61, v62, v63
	ds_write_b64 v136, v[60:61]
	s_waitcnt lgkmcnt(2)
; DEV u32x2 pk4(f32x4 v) { u32x2 r = {pk_bf16(v[0], v[1]), pk_bf16(v[2], v[3])}; return r; }
; DEV f32x4 unpk4(u32x2 u) { f32x4 r = {bf_lo(u[0]), bf_hi(u[0]), bf_lo(u[1]), bf_hi(u[1])}; return r; }
;   DEV void operator()(f32x4 (&acc)[2][2][4][2], int brow, int bcol, int wr, int wc, int fr, int fq) const {
;     ...
;     for (int ai = 0; ai < 2; ++ai)
; #pragma unroll
;       for (int m = 0; m < 4; ++m) {
;         const int rl = ai * 128 + wr * 64 + m * 16 + fr, tok = brow + rl;
; #pragma unroll
;         for (int bj = 0; bj < 2; ++bj)
; #pragma unroll
;           for (int n = 0; n < 2; ++n) {
;             const int cl = bj * 128 + wc * 32 + n * 16 + fq * 4, col = bcol + cl;
;             const int f = ((ai * 4 + m) * 2 + bj) * 2 + n;
;             const f32x4 g = unpk4(tile_get4(rl, cl));
;             f32x4 v = acc[ai][bj][m][n] * g;
;             if (step == 0) sp[(size_t)f * 512] = pk4(v);
;             else if (step == 1) sp[(size_t)f * 512] = pk4(unpk4(sp[(size_t)f * 512]) + v);
;             else tile_put4(rl, cl, pk4(unpk4(sp[(size_t)f * 512]) + v));
	v_lshlrev_b32_e32 v146, 16, v246
	v_and_b32_e32 v147, 0xffff0000, v246
	v_lshlrev_b32_e32 v148, 16, v247
	v_and_b32_e32 v149, 0xffff0000, v247
	v_pk_mul_f32 v[56:57], v[56:57], v[146:147]
	v_pk_mul_f32 v[58:59], v[58:59], v[148:149]
	v_lshlrev_b32_e32 v150, 16, v206
	v_and_b32_e32 v151, 0xffff0000, v206
	v_lshlrev_b32_e32 v152, 16, v207
	v_and_b32_e32 v153, 0xffff0000, v207
	v_pk_add_f32 v[56:57], v[56:57], v[150:151]
	v_pk_add_f32 v[58:59], v[58:59], v[152:153]
	v_cvt_pk_bf16_f32 v62, v56, v57
	v_cvt_pk_bf16_f32 v63, v58, v59
	ds_write_b64 v137, v[62:63]
	s_waitcnt lgkmcnt(1)
	v_lshlrev_b32_e32 v146, 16, v248
	v_and_b32_e32 v147, 0xffff0000, v248
	v_lshlrev_b32_e32 v148, 16, v249
	v_and_b32_e32 v149, 0xffff0000, v249
	v_pk_mul_f32 v[52:53], v[52:53], v[146:147]
	v_pk_mul_f32 v[54:55], v[54:55], v[148:149]
	v_lshlrev_b32_e32 v150, 16, v208
	v_and_b32_e32 v151, 0xffff0000, v208
	v_lshlrev_b32_e32 v152, 16, v209
	v_and_b32_e32 v153, 0xffff0000, v209
	v_pk_add_f32 v[52:53], v[52:53], v[150:151]
	v_pk_add_f32 v[54:55], v[54:55], v[152:153]
	v_cvt_pk_bf16_f32 v52, v52, v53
	v_cvt_pk_bf16_f32 v53, v54, v55
	ds_write_b64 v136, v[52:53] offset:256
	s_waitcnt lgkmcnt(0)
	v_lshlrev_b32_e32 v146, 16, v250
	v_and_b32_e32 v147, 0xffff0000, v250
	v_lshlrev_b32_e32 v148, 16, v251
	v_and_b32_e32 v149, 0xffff0000, v251
	v_pk_mul_f32 v[48:49], v[48:49], v[146:147]
	v_pk_mul_f32 v[50:51], v[50:51], v[148:149]
	v_lshlrev_b32_e32 v150, 16, v210
	v_and_b32_e32 v151, 0xffff0000, v210
	v_lshlrev_b32_e32 v152, 16, v211
	v_and_b32_e32 v153, 0xffff0000, v211
	v_pk_add_f32 v[48:49], v[48:49], v[150:151]
	v_pk_add_f32 v[50:51], v[50:51], v[152:153]
	v_cvt_pk_bf16_f32 v54, v48, v49
	v_cvt_pk_bf16_f32 v55, v50, v51
	ds_write_b64 v137, v[54:55] offset:256
	ds_read_b64 v[244:245], v136 offset:8448
	ds_read_b64 v[246:247], v137 offset:8448
	ds_read_b64 v[248:249], v136 offset:8192
	ds_read_b64 v[250:251], v137 offset:8192
	s_waitcnt lgkmcnt(3)
	v_lshlrev_b32_e32 v146, 16, v244
	v_and_b32_e32 v147, 0xffff0000, v244
	v_lshlrev_b32_e32 v148, 16, v245
	v_and_b32_e32 v149, 0xffff0000, v245
	v_pk_mul_f32 v[44:45], v[44:45], v[146:147]
	v_pk_mul_f32 v[46:47], v[46:47], v[148:149]
	v_lshlrev_b32_e32 v150, 16, v212
	v_and_b32_e32 v151, 0xffff0000, v212
	v_lshlrev_b32_e32 v152, 16, v213
	v_and_b32_e32 v153, 0xffff0000, v213
	v_pk_add_f32 v[44:45], v[44:45], v[150:151]
	v_pk_add_f32 v[46:47], v[46:47], v[152:153]
	v_cvt_pk_bf16_f32 v44, v44, v45
	v_cvt_pk_bf16_f32 v45, v46, v47
	ds_write_b64 v136, v[44:45] offset:8448
	s_waitcnt lgkmcnt(2)
	v_lshlrev_b32_e32 v146, 16, v246
	v_and_b32_e32 v147, 0xffff0000, v246
	v_lshlrev_b32_e32 v148, 16, v247
	v_and_b32_e32 v149, 0xffff0000, v247
	v_pk_mul_f32 v[40:41], v[40:41], v[146:147]
	v_pk_mul_f32 v[42:43], v[42:43], v[148:149]
	v_lshlrev_b32_e32 v150, 16, v214
	v_and_b32_e32 v151, 0xffff0000, v214
	v_lshlrev_b32_e32 v152, 16, v215
	v_and_b32_e32 v153, 0xffff0000, v215
	v_pk_add_f32 v[40:41], v[40:41], v[150:151]
	v_pk_add_f32 v[42:43], v[42:43], v[152:153]
	v_cvt_pk_bf16_f32 v46, v40, v41
	v_cvt_pk_bf16_f32 v47, v42, v43
	ds_write_b64 v137, v[46:47] offset:8448
	s_waitcnt lgkmcnt(1)
	v_lshlrev_b32_e32 v146, 16, v248
	v_and_b32_e32 v147, 0xffff0000, v248
	v_lshlrev_b32_e32 v148, 16, v249
	v_and_b32_e32 v149, 0xffff0000, v249
	v_pk_mul_f32 v[36:37], v[36:37], v[146:147]
	v_pk_mul_f32 v[38:39], v[38:39], v[148:149]
	v_lshlrev_b32_e32 v150, 16, v224
	v_and_b32_e32 v151, 0xffff0000, v224
	v_lshlrev_b32_e32 v152, 16, v225
	v_and_b32_e32 v153, 0xffff0000, v225
	v_pk_add_f32 v[36:37], v[36:37], v[150:151]
	v_pk_add_f32 v[38:39], v[38:39], v[152:153]
	v_cvt_pk_bf16_f32 v36, v36, v37
	v_cvt_pk_bf16_f32 v37, v38, v39
	ds_write_b64 v136, v[36:37] offset:8192
	s_waitcnt lgkmcnt(0)
	v_lshlrev_b32_e32 v146, 16, v250
	v_and_b32_e32 v147, 0xffff0000, v250
	v_lshlrev_b32_e32 v148, 16, v251
	v_and_b32_e32 v149, 0xffff0000, v251
	v_pk_mul_f32 v[32:33], v[32:33], v[146:147]
	v_pk_mul_f32 v[34:35], v[34:35], v[148:149]
	v_lshlrev_b32_e32 v150, 16, v226
	v_and_b32_e32 v151, 0xffff0000, v226
	v_lshlrev_b32_e32 v152, 16, v227
	v_and_b32_e32 v153, 0xffff0000, v227
	v_pk_add_f32 v[32:33], v[32:33], v[150:151]
	v_pk_add_f32 v[34:35], v[34:35], v[152:153]
	v_cvt_pk_bf16_f32 v38, v32, v33
	v_cvt_pk_bf16_f32 v39, v34, v35
	ds_write_b64 v137, v[38:39] offset:8192
	ds_read_b64 v[244:245], v136 offset:16384
	ds_read_b64 v[246:247], v137 offset:16384
	ds_read_b64 v[248:249], v136 offset:16640
	ds_read_b64 v[250:251], v137 offset:16640
	s_waitcnt lgkmcnt(3)
	v_lshlrev_b32_e32 v146, 16, v244
	v_and_b32_e32 v147, 0xffff0000, v244
	v_lshlrev_b32_e32 v148, 16, v245
	v_and_b32_e32 v149, 0xffff0000, v245
	v_pk_mul_f32 v[28:29], v[28:29], v[146:147]
	v_pk_mul_f32 v[30:31], v[30:31], v[148:149]
	v_lshlrev_b32_e32 v150, 16, v228
	v_and_b32_e32 v151, 0xffff0000, v228
	v_lshlrev_b32_e32 v152, 16, v229
	v_and_b32_e32 v153, 0xffff0000, v229
	v_pk_add_f32 v[28:29], v[28:29], v[150:151]
	v_pk_add_f32 v[30:31], v[30:31], v[152:153]
	v_cvt_pk_bf16_f32 v28, v28, v29
	v_cvt_pk_bf16_f32 v29, v30, v31
	ds_write_b64 v136, v[28:29] offset:16384
	s_waitcnt lgkmcnt(2)
	v_lshlrev_b32_e32 v146, 16, v246
	v_and_b32_e32 v147, 0xffff0000, v246
	v_lshlrev_b32_e32 v148, 16, v247
	v_and_b32_e32 v149, 0xffff0000, v247
	v_pk_mul_f32 v[24:25], v[24:25], v[146:147]
	v_pk_mul_f32 v[26:27], v[26:27], v[148:149]
	v_lshlrev_b32_e32 v150, 16, v230
	v_and_b32_e32 v151, 0xffff0000, v230
	v_lshlrev_b32_e32 v152, 16, v231
	v_and_b32_e32 v153, 0xffff0000, v231
	v_pk_add_f32 v[24:25], v[24:25], v[150:151]
	v_pk_add_f32 v[26:27], v[26:27], v[152:153]
	v_cvt_pk_bf16_f32 v30, v24, v25
	v_cvt_pk_bf16_f32 v31, v26, v27
	ds_write_b64 v137, v[30:31] offset:16384
	s_waitcnt lgkmcnt(1)
; DEV u32x2 pk4(f32x4 v) { u32x2 r = {pk_bf16(v[0], v[1]), pk_bf16(v[2], v[3])}; return r; }
; DEV f32x4 unpk4(u32x2 u) { f32x4 r = {bf_lo(u[0]), bf_hi(u[0]), bf_lo(u[1]), bf_hi(u[1])}; return r; }
;   DEV void operator()(f32x4 (&acc)[2][2][4][2], int brow, int bcol, int wr, int wc, int fr, int fq) const {
;     ...
;     for (int ai = 0; ai < 2; ++ai)
; #pragma unroll
;       for (int m = 0; m < 4; ++m) {
;         const int rl = ai * 128 + wr * 64 + m * 16 + fr, tok = brow + rl;
; #pragma unroll
;         for (int bj = 0; bj < 2; ++bj)
; #pragma unroll
;           for (int n = 0; n < 2; ++n) {
;             const int cl = bj * 128 + wc * 32 + n * 16 + fq * 4, col = bcol + cl;
;             const int f = ((ai * 4 + m) * 2 + bj) * 2 + n;
;             const f32x4 g = unpk4(tile_get4(rl, cl));
;             f32x4 v = acc[ai][bj][m][n] * g;
;             if (step == 0) sp[(size_t)f * 512] = pk4(v);
;             else if (step == 1) sp[(size_t)f * 512] = pk4(unpk4(sp[(size_t)f * 512]) + v);
;             else tile_put4(rl, cl, pk4(unpk4(sp[(size_t)f * 512]) + v));
;           }
;       }
;     if (step == 2) {
;       __syncthreads();
;       tile_rows_out(mbf + (size_t)brow * 2048 + bcol, 2048, tid);
	v_lshlrev_b32_e32 v146, 16, v248
	v_and_b32_e32 v147, 0xffff0000, v248
	v_lshlrev_b32_e32 v148, 16, v249
	v_and_b32_e32 v149, 0xffff0000, v249
	v_pk_mul_f32 v[20:21], v[20:21], v[146:147]
	v_pk_mul_f32 v[22:23], v[22:23], v[148:149]
	v_lshlrev_b32_e32 v150, 16, v232
	v_and_b32_e32 v151, 0xffff0000, v232
	v_lshlrev_b32_e32 v152, 16, v233
	v_and_b32_e32 v153, 0xffff0000, v233
	v_pk_add_f32 v[20:21], v[20:21], v[150:151]
	v_pk_add_f32 v[22:23], v[22:23], v[152:153]
	v_cvt_pk_bf16_f32 v20, v20, v21
	v_cvt_pk_bf16_f32 v21, v22, v23
	ds_write_b64 v136, v[20:21] offset:16640
	s_waitcnt lgkmcnt(0)
	v_lshlrev_b32_e32 v146, 16, v250
	v_and_b32_e32 v147, 0xffff0000, v250
	v_lshlrev_b32_e32 v148, 16, v251
	v_and_b32_e32 v149, 0xffff0000, v251
	v_pk_mul_f32 v[16:17], v[16:17], v[146:147]
	v_pk_mul_f32 v[18:19], v[18:19], v[148:149]
	v_lshlrev_b32_e32 v150, 16, v234
	v_and_b32_e32 v151, 0xffff0000, v234
	v_lshlrev_b32_e32 v152, 16, v235
	v_and_b32_e32 v153, 0xffff0000, v235
	v_pk_add_f32 v[16:17], v[16:17], v[150:151]
	v_pk_add_f32 v[18:19], v[18:19], v[152:153]
	v_cvt_pk_bf16_f32 v22, v16, v17
	v_cvt_pk_bf16_f32 v23, v18, v19
	ds_write_b64 v137, v[22:23] offset:16640
	ds_read_b64 v[244:245], v136 offset:24832
	ds_read_b64 v[246:247], v137 offset:24832
	ds_read_b64 v[248:249], v136 offset:24576
	ds_read_b64 v[250:251], v137 offset:24576
	s_waitcnt lgkmcnt(3)
	v_lshlrev_b32_e32 v146, 16, v244
	v_and_b32_e32 v147, 0xffff0000, v244
	v_lshlrev_b32_e32 v148, 16, v245
	v_and_b32_e32 v149, 0xffff0000, v245
	v_pk_mul_f32 v[12:13], v[12:13], v[146:147]
	v_pk_mul_f32 v[14:15], v[14:15], v[148:149]
	v_lshlrev_b32_e32 v150, 16, v236
	v_and_b32_e32 v151, 0xffff0000, v236
	v_lshlrev_b32_e32 v152, 16, v237
	v_and_b32_e32 v153, 0xffff0000, v237
	v_pk_add_f32 v[12:13], v[12:13], v[150:151]
	v_pk_add_f32 v[14:15], v[14:15], v[152:153]
	v_cvt_pk_bf16_f32 v12, v12, v13
	v_cvt_pk_bf16_f32 v13, v14, v15
	ds_write_b64 v136, v[12:13] offset:24832
	s_waitcnt lgkmcnt(2)
	v_lshlrev_b32_e32 v146, 16, v246
	v_and_b32_e32 v147, 0xffff0000, v246
	v_lshlrev_b32_e32 v148, 16, v247
	v_and_b32_e32 v149, 0xffff0000, v247
	v_pk_mul_f32 v[8:9], v[8:9], v[146:147]
	v_pk_mul_f32 v[10:11], v[10:11], v[148:149]
	v_lshlrev_b32_e32 v150, 16, v238
	v_and_b32_e32 v151, 0xffff0000, v238
	v_lshlrev_b32_e32 v152, 16, v239
	v_and_b32_e32 v153, 0xffff0000, v239
	v_pk_add_f32 v[8:9], v[8:9], v[150:151]
	v_pk_add_f32 v[10:11], v[10:11], v[152:153]
	v_cvt_pk_bf16_f32 v14, v8, v9
	v_cvt_pk_bf16_f32 v15, v10, v11
	ds_write_b64 v137, v[14:15] offset:24832
	s_waitcnt lgkmcnt(1)
	v_lshlrev_b32_e32 v146, 16, v248
	v_and_b32_e32 v147, 0xffff0000, v248
	v_lshlrev_b32_e32 v148, 16, v249
	v_and_b32_e32 v149, 0xffff0000, v249
	v_pk_mul_f32 v[4:5], v[4:5], v[146:147]
	v_pk_mul_f32 v[6:7], v[6:7], v[148:149]
	v_lshlrev_b32_e32 v150, 16, v240
	v_and_b32_e32 v151, 0xffff0000, v240
	v_lshlrev_b32_e32 v152, 16, v241
	v_and_b32_e32 v153, 0xffff0000, v241
	v_pk_add_f32 v[4:5], v[4:5], v[150:151]
	v_pk_add_f32 v[6:7], v[6:7], v[152:153]
	v_cvt_pk_bf16_f32 v4, v4, v5
	v_cvt_pk_bf16_f32 v5, v6, v7
	ds_write_b64 v136, v[4:5] offset:24576
	s_waitcnt lgkmcnt(0)
	v_lshlrev_b32_e32 v146, 16, v250
	v_and_b32_e32 v147, 0xffff0000, v250
	v_lshlrev_b32_e32 v148, 16, v251
	v_and_b32_e32 v149, 0xffff0000, v251
	v_pk_mul_f32 v[0:1], v[0:1], v[146:147]
	v_pk_mul_f32 v[2:3], v[2:3], v[148:149]
	v_lshlrev_b32_e32 v150, 16, v242
	v_and_b32_e32 v151, 0xffff0000, v242
	v_lshlrev_b32_e32 v152, 16, v243
	v_and_b32_e32 v153, 0xffff0000, v243
	v_pk_add_f32 v[0:1], v[0:1], v[150:151]
	v_pk_add_f32 v[2:3], v[2:3], v[152:153]
	v_cvt_pk_bf16_f32 v6, v0, v1
	v_cvt_pk_bf16_f32 v7, v2, v3
	ds_write_b64 v137, v[6:7] offset:24576
	s_lshl_b32 s16, s4, 12
	s_lshl_b32 s17, s34, 1
	s_add_i32 s16, s16, s17
	s_add_u32 s14, s79, s16
	s_addc_u32 s15, s89, 0
	v_lshrrev_b32_e32 v144, 5, v140
	v_and_b32_e32 v145, 31, v140
	v_xor_b32_e32 v145, v145, v144
	v_lshlrev_b32_e32 v156, 12, v144
	v_mov_b32_e32 v157, v156
	v_lshl_add_u32 v156, v145, 4, v156
	v_xor_b32_e32 v145, 16, v145
	v_lshl_add_u32 v157, v145, 4, v157
	v_add_u32_e32 v157, 0x10000, v157
	v_lshlrev_b32_e32 v154, 4, v140
	v_add_u32_e32 v155, 0x10000, v154
	s_waitcnt lgkmcnt(0)
	s_barrier
; DEV u32x2 pk4(f32x4 v) { u32x2 r = {pk_bf16(v[0], v[1]), pk_bf16(v[2], v[3])}; return r; }
; DEV f32x4 unpk4(u32x2 u) { f32x4 r = {bf_lo(u[0]), bf_hi(u[0]), bf_lo(u[1]), bf_hi(u[1])}; return r; }
; template <bool NT = false>
; DEV void tile_rows_out(bf16_t* __restrict__ out0, const size_t ld, const int tid) {
; #pragma unroll
;   for (int i = 0; i < 16; ++i) {
;     const int id = i * 512 + tid, r = id >> 5, pos = id & 31, c = pos ^ (r & 31);
;     const u32x4 v = *(const u32x4*)(smem + r * 512 + pos * 16);
;     if (NT) __builtin_nontemporal_store(v, (u32x4*)(out0 + (size_t)r * ld + 8 * c)); else *(u32x4*)(out0 + (size_t)r * ld + 8 * c) = v;
;   }
;   DEV void operator()(f32x4 (&acc)[2][2][4][2], int brow, int bcol, int wr, int wc, int fr, int fq) const {
;     ...
;             if (step == 0) sp[(size_t)f * 512] = pk4(v);
;             else if (step == 1) sp[(size_t)f * 512] = pk4(unpk4(sp[(size_t)f * 512]) + v);
	ds_read_b128 v[0:3], v154
	ds_read_b128 v[4:7], v154 offset:8192
	ds_read_b128 v[8:11], v154 offset:16384
	ds_read_b128 v[12:15], v154 offset:24576
	ds_read_b128 v[16:19], v154 offset:32768
	ds_read_b128 v[20:23], v154 offset:40960
	ds_read_b128 v[24:27], v154 offset:49152
	ds_read_b128 v[28:31], v154 offset:57344
	ds_read_b128 v[32:35], v155
	ds_read_b128 v[36:39], v155 offset:8192
	ds_read_b128 v[40:43], v155 offset:16384
	ds_read_b128 v[44:47], v155 offset:24576
	ds_read_b128 v[48:51], v155 offset:32768
	ds_read_b128 v[52:55], v155 offset:40960
	ds_read_b128 v[56:59], v155 offset:49152
	ds_read_b128 v[60:63], v155 offset:57344
	s_waitcnt lgkmcnt(15)
	global_store_dwordx4 v156, v[0:3], s[14:15] sc1
	v_add_u32_e32 v156, 0x20000, v156
	s_waitcnt lgkmcnt(14)
	global_store_dwordx4 v157, v[4:7], s[14:15] sc1
	v_add_u32_e32 v157, 0x20000, v157
	s_waitcnt lgkmcnt(13)
	global_store_dwordx4 v156, v[8:11], s[14:15] sc1
	v_add_u32_e32 v156, 0x20000, v156
	s_waitcnt lgkmcnt(12)
	global_store_dwordx4 v157, v[12:15], s[14:15] sc1
	v_add_u32_e32 v157, 0x20000, v157
	s_waitcnt lgkmcnt(11)
	global_store_dwordx4 v156, v[16:19], s[14:15] sc1
	v_add_u32_e32 v156, 0x20000, v156
	s_waitcnt lgkmcnt(10)
	global_store_dwordx4 v157, v[20:23], s[14:15] sc1
	v_add_u32_e32 v157, 0x20000, v157
	s_waitcnt lgkmcnt(9)
	global_store_dwordx4 v156, v[24:27], s[14:15] sc1
	v_add_u32_e32 v156, 0x20000, v156
	s_waitcnt lgkmcnt(8)
	global_store_dwordx4 v157, v[28:31], s[14:15] sc1
	v_add_u32_e32 v157, 0x20000, v157
	s_waitcnt lgkmcnt(7)
	global_store_dwordx4 v156, v[32:35], s[14:15] sc1
	v_add_u32_e32 v156, 0x20000, v156
	s_waitcnt lgkmcnt(6)
	global_store_dwordx4 v157, v[36:39], s[14:15] sc1
	v_add_u32_e32 v157, 0x20000, v157
	s_waitcnt lgkmcnt(5)
	global_store_dwordx4 v156, v[40:43], s[14:15] sc1
	v_add_u32_e32 v156, 0x20000, v156
	s_waitcnt lgkmcnt(4)
	global_store_dwordx4 v157, v[44:47], s[14:15] sc1
	v_add_u32_e32 v157, 0x20000, v157
	s_waitcnt lgkmcnt(3)
	global_store_dwordx4 v156, v[48:51], s[14:15] sc1
	v_add_u32_e32 v156, 0x20000, v156
	s_waitcnt lgkmcnt(2)
	global_store_dwordx4 v157, v[52:55], s[14:15] sc1
	v_add_u32_e32 v157, 0x20000, v157
	s_waitcnt lgkmcnt(1)
	global_store_dwordx4 v156, v[56:59], s[14:15] sc1
	s_waitcnt lgkmcnt(0)
	global_store_dwordx4 v157, v[60:63], s[14:15] sc1
	s_branch .LBB0_1551
	s_cmp_lt_i32 s37, 1
	s_cbranch_scc1 .Lp3_nopf
	v_readlane_b32 s22, v253, 10
	s_ashr_i32 s21, s4, 5
	s_and_b32 s21, s21, -8
	s_ashr_i32 s20, s34, 8
	s_add_i32 s20, s21, s20
	s_ashr_i32 s21, s20, 31
	s_lshl_b64 s[20:21], s[20:21], 17
	s_add_u32 s20, s76, s20
	s_addc_u32 s21, s22, s21
	v_lshlrev_b32_e32 v158, 3, v140
	global_load_dwordx2 v[160:161], v158, s[20:21]
	v_add_u32_e32 v158, 0x1000, v158
	global_load_dwordx2 v[162:163], v158, s[20:21]
	v_add_u32_e32 v158, 0x1000, v158
	global_load_dwordx2 v[164:165], v158, s[20:21]
	v_add_u32_e32 v158, 0x1000, v158
	global_load_dwordx2 v[166:167], v158, s[20:21]
	v_add_u32_e32 v158, 0x1000, v158
	global_load_dwordx2 v[168:169], v158, s[20:21]
	v_add_u32_e32 v158, 0x1000, v158
	global_load_dwordx2 v[170:171], v158, s[20:21]
	v_add_u32_e32 v158, 0x1000, v158
	global_load_dwordx2 v[172:173], v158, s[20:21]
	v_add_u32_e32 v158, 0x1000, v158
	global_load_dwordx2 v[174:175], v158, s[20:21]
	v_add_u32_e32 v158, 0x1000, v158
	global_load_dwordx2 v[184:185], v158, s[20:21]
	v_add_u32_e32 v158, 0x1000, v158
	global_load_dwordx2 v[186:187], v158, s[20:21]
	v_add_u32_e32 v158, 0x1000, v158
	global_load_dwordx2 v[188:189], v158, s[20:21]
	v_add_u32_e32 v158, 0x1000, v158
	global_load_dwordx2 v[190:191], v158, s[20:21]
	v_add_u32_e32 v158, 0x1000, v158
	global_load_dwordx2 v[192:193], v158, s[20:21]
	v_add_u32_e32 v158, 0x1000, v158
	global_load_dwordx2 v[194:195], v158, s[20:21]
	v_add_u32_e32 v158, 0x1000, v158
	global_load_dwordx2 v[196:197], v158, s[20:21]
	v_add_u32_e32 v158, 0x1000, v158
	global_load_dwordx2 v[200:201], v158, s[20:21]
	v_add_u32_e32 v158, 0x1000, v158
	global_load_dwordx2 v[202:203], v158, s[20:21]
	v_add_u32_e32 v158, 0x1000, v158
	global_load_dwordx2 v[204:205], v158, s[20:21]
	v_add_u32_e32 v158, 0x1000, v158
	global_load_dwordx2 v[206:207], v158, s[20:21]
	v_add_u32_e32 v158, 0x1000, v158
	global_load_dwordx2 v[208:209], v158, s[20:21]
	v_add_u32_e32 v158, 0x1000, v158
	global_load_dwordx2 v[210:211], v158, s[20:21]
	v_add_u32_e32 v158, 0x1000, v158
	global_load_dwordx2 v[212:213], v158, s[20:21]
	v_add_u32_e32 v158, 0x1000, v158
	global_load_dwordx2 v[214:215], v158, s[20:21]
	v_add_u32_e32 v158, 0x1000, v158
	global_load_dwordx2 v[216:217], v158, s[20:21]
	v_add_u32_e32 v158, 0x1000, v158
	global_load_dwordx2 v[224:225], v158, s[20:21]
	v_add_u32_e32 v158, 0x1000, v158
	global_load_dwordx2 v[226:227], v158, s[20:21]
	v_add_u32_e32 v158, 0x1000, v158
	global_load_dwordx2 v[228:229], v158, s[20:21]
	v_add_u32_e32 v158, 0x1000, v158
	global_load_dwordx2 v[230:231], v158, s[20:21]
	v_add_u32_e32 v158, 0x1000, v158
	global_load_dwordx2 v[232:233], v158, s[20:21]
	v_add_u32_e32 v158, 0x1000, v158
	global_load_dwordx2 v[234:235], v158, s[20:21]
	v_add_u32_e32 v158, 0x1000, v158
	global_load_dwordx2 v[236:237], v158, s[20:21]
	v_add_u32_e32 v158, 0x1000, v158
	global_load_dwordx2 v[238:239], v158, s[20:21]
